# FFN-up sample-tile epilogue (last round): 256 dead zero-initialisations in front of full-mask row_ror DPP moves deleted, wait states re-padded
# baseline (speedup 1.0000x reference)
; __device__ __forceinline__ float dpp_ror1(float v) { return __builtin_bit_cast(float, __builtin_amdgcn_update_dpp(0, __builtin_bit_cast(int, v), 0x121, 0xf, 0xf, false)); }
; __device__ __forceinline__ float dpp_ror2(float v) { return __builtin_bit_cast(float, __builtin_amdgcn_update_dpp(0, __builtin_bit_cast(int, v), 0x122, 0xf, 0xf, false)); }
;     __device__ __forceinline__ void operator()(f32x4 (&acc)[2][2][4][2], const pg8::Unit& u, int wr, int wc, int fr, int fq) const {
;     ...
;             for (int n = 0; n < 2; ++n) {
;                 const f32x4 w0 = *(const f32x4*)(cw + ch0 + 4 * n), w1 = *(const f32x4*)(cw + DFF + ch0 + 4 * n), w2 = *(const f32x4*)(cw + 2 * DFF + ch0 + 4 * n), bb = *(const f32x4*)(cb + ch0 + 4 * n);
; #pragma unroll
;                 for (int m = 0; m < 4; ++m) { const int row = row0 + ai * 128 + m * 16; const f32x4 g = acc[ai][0][m][n], vv = acc[ai][1][m][n]; f32x4 p1, p2;
;                     if (prompt) { const f32x4 gp = (m == 0) ? hal[n] : acc[ai][0][m > 0 ? m - 1 : 0][n];
; #pragma unroll
;                         for (int j = 0; j < 4; ++j) { p1[j] = dpp_ror1(fr == 15 ? gp[j] : g[j]); p2[j] = dpp_ror2(fr >= 14 ? gp[j] : g[j]); } }
.LBB0_2604:
	v_readlane_b32 s40, v254, 41
	v_readlane_b32 s41, v254, 42
	v_readlane_b32 s42, v254, 43
	v_readlane_b32 s43, v254, 44
	v_readlane_b32 s44, v254, 45
	v_readlane_b32 s45, v254, 46
	v_readlane_b32 s46, v254, 47
	v_readlane_b32 s47, v254, 48
	s_mov_b64 s[40:41], s[44:45]
	v_lshlrev_b64 v[150:151], 2, v[194:195]
	s_mov_b64 s[42:43], s[46:47]
	v_lshl_add_u64 v[202:203], s[40:41], 0, v[150:151]
	v_lshl_add_u64 v[216:217], s[22:23], 0, v[150:151]
	v_lshl_add_u64 v[204:205], s[42:43], 0, v[150:151]
	v_lshl_add_u64 v[214:215], s[6:7], 0, v[150:151]
	global_load_dwordx4 v[146:149], v[202:203], off
	global_load_dwordx4 v[142:145], v[214:215], off
	global_load_dwordx4 v[154:157], v[216:217], off
	global_load_dwordx4 v[150:153], v[204:205], off
	s_and_b64 vcc, exec, s[20:21]
	s_mov_b64 s[2:3], -1
	v_readlane_b32 s48, v254, 49
	v_readlane_b32 s49, v254, 50
	v_readlane_b32 s50, v254, 51
	v_readlane_b32 s51, v254, 52
	v_readlane_b32 s52, v254, 53
	v_readlane_b32 s53, v254, 54
	v_readlane_b32 s54, v254, 55
	v_readlane_b32 s55, v254, 56
	s_cbranch_vccnz .LBB0_2606
	s_waitcnt vmcnt(7) lgkmcnt(1)
	v_cndmask_b32_e64 v163, v134, v158, s[16:17]
	v_cndmask_b32_e64 v158, v158, v134, s[38:39]
	s_nop 0
	v_mov_b32_dpp v162, v163 row_ror:1 row_mask:0xf bank_mask:0xf
	v_mov_b32_dpp v227, v158 row_ror:2 row_mask:0xf bank_mask:0xf
	v_cndmask_b32_e64 v158, v135, v159, s[16:17]
	s_nop 1
	v_mov_b32_dpp v163, v158 row_ror:1 row_mask:0xf bank_mask:0xf
	v_cndmask_b32_e64 v158, v159, v135, s[38:39]
	s_nop 1
	v_mov_b32_dpp v225, v158 row_ror:2 row_mask:0xf bank_mask:0xf
	s_waitcnt vmcnt(6)
	v_cndmask_b32_e64 v158, v136, v160, s[16:17]
	s_mov_b64 s[2:3], 0
	s_nop 0
	v_mov_b32_dpp v164, v158 row_ror:1 row_mask:0xf bank_mask:0xf
	v_cndmask_b32_e64 v158, v160, v136, s[38:39]
	v_mov_b32_e32 v230, v134
	v_mov_b32_e32 v228, v135
	v_mov_b32_dpp v221, v158 row_ror:2 row_mask:0xf bank_mask:0xf
	v_cndmask_b32_e64 v158, v137, v161, s[16:17]
	v_mov_b32_e32 v226, v136
	v_mov_b32_e32 v224, v137
	v_mov_b32_dpp v165, v158 row_ror:1 row_mask:0xf bank_mask:0xf
	v_cndmask_b32_e64 v158, v161, v137, s[38:39]
	s_nop 1
	v_mov_b32_dpp v223, v158 row_ror:2 row_mask:0xf bank_mask:0xf

; __device__ __forceinline__ unsigned cvt_pk_bf16(float lo, float hi) { unsigned r; asm("v_cvt_pk_bf16_f32 %0, %1, %2" : "=v"(r) : "v"(lo), "v"(hi)); return r; }
;     __device__ __forceinline__ void operator()(f32x4 (&acc)[2][2][4][2], const pg8::Unit& u, int wr, int wc, int fr, int fq) const {
;     ...
;                 for (int n = 0; n < 2; ++n) { const u32x4 c = *(const u32x4*)(cmax + u.pn * 256 + bj * 128 + cl0 + 4 * n); sw[bj][n] = (f32x4){__uint_as_float(c.x), __uint_as_float(c.y), __uint_as_float(c.z), __uint_as_float(c.w)} * (1.004f / 127.0f); }
; #pragma unroll
;             for (int ai = 0; ai < 2; ++ai)
; #pragma unroll
;                 for (int m = 0; m < 4; ++m)
; #pragma unroll
;                     for (int bj = 0; bj < 2; ++bj)
; #pragma unroll
;                         for (int n = 0; n < 2; ++n) { const i32x4 q = __builtin_bit_cast(i32x4, acc[ai][bj][m][n]); acc[ai][bj][m][n] = (f32x4){(float)q[0], (float)q[1], (float)q[2], (float)q[3]} * sw[bj][n] * sc[ai][m]; }
;     ...
;                 for (int m = 0; m < 4; ++m) { const int row = row0 + ai * 128 + m * 16; const f32x4 g = acc[ai][0][m][n], vv = acc[ai][1][m][n]; f32x4 p1, p2;
;                     if (prompt) { const f32x4 gp = (m == 0) ? hal[n] : acc[ai][0][m > 0 ? m - 1 : 0][n];
; #pragma unroll
;                         for (int j = 0; j < 4; ++j) { p1[j] = dpp_ror1(fr == 15 ? gp[j] : g[j]); p2[j] = dpp_ror2(fr >= 14 ? gp[j] : g[j]); } }
;                     else { const int t = fr & 3; const float* sp = stf + (size_t)((row - MP) >> 2) * 2 * DFF + ch0 + 4 * n;
;                         f32x4 b0 = (f32x4){0.f, 0.f, 0.f, 0.f}, b1 = b0; if (t == 0) b0 = *(const f32x4*)sp; if (t <= 1) b1 = *(const f32x4*)(sp + DFF);
; #pragma unroll
;                         for (int j = 0; j < 4; ++j) { const float r1 = dpp_ror1(g[j]), r2 = dpp_ror2(g[j]); p1[j] = t >= 1 ? r1 : b1[j]; p2[j] = t >= 2 ? r2 : (t == 1 ? b1[j] : b0[j]); } }
;                     float o[4];
; #pragma unroll
;                     for (int j = 0; j < 4; ++j) { const float y = bb[j] + w0[j] * p2[j] + w1[j] * p1[j] + w2[j] * g[j]; o[j] = gelu_tanh(y) * vv[j]; }
;                     u32x2 w; w.x = cvt_pk_bf16(o[0], o[1]); w.y = cvt_pk_bf16(o[2], o[3]);
;                     *(u32x2*)(ACT + (size_t)row * DFF + ch0 + 4 * n) = w; } } }
.LBB0_2611:
	s_or_b64 exec, exec, s[2:3]
	s_waitcnt vmcnt(0)
	v_cndmask_b32_e64 v158, v158, v164, s[14:15]
	v_mov_b32_dpp v163, v134 row_ror:2 row_mask:0xf bank_mask:0xf
	v_mov_b32_dpp v162, v134 row_ror:1 row_mask:0xf bank_mask:0xf
	v_cndmask_b32_e64 v227, v158, v163, s[12:13]
	v_cndmask_b32_e64 v162, v162, v164, s[10:11]
	v_mov_b32_dpp v158, v135 row_ror:1 row_mask:0xf bank_mask:0xf
	v_cndmask_b32_e64 v163, v158, v165, s[10:11]
	v_mov_b32_dpp v164, v135 row_ror:2 row_mask:0xf bank_mask:0xf
	v_cndmask_b32_e64 v158, v159, v165, s[14:15]
	v_cndmask_b32_e64 v225, v158, v164, s[12:13]
	v_mov_b32_e32 v230, v134
	v_mov_b32_dpp v158, v136 row_ror:1 row_mask:0xf bank_mask:0xf
	v_mov_b32_dpp v159, v136 row_ror:2 row_mask:0xf bank_mask:0xf
	v_cndmask_b32_e64 v164, v158, v166, s[10:11]
	v_cndmask_b32_e64 v158, v160, v166, s[14:15]
	v_cndmask_b32_e64 v221, v158, v159, s[12:13]
	v_mov_b32_e32 v228, v135
	v_mov_b32_dpp v158, v137 row_ror:1 row_mask:0xf bank_mask:0xf
	v_mov_b32_dpp v159, v137 row_ror:2 row_mask:0xf bank_mask:0xf
	v_cndmask_b32_e64 v165, v158, v167, s[10:11]
	v_cndmask_b32_e64 v158, v161, v167, s[14:15]
	v_cndmask_b32_e64 v223, v158, v159, s[12:13]
	v_mov_b32_e32 v226, v136
	v_mov_b32_e32 v224, v137
.LBB0_2612:
	s_waitcnt vmcnt(1)
	v_mov_b32_e32 v166, v154
	v_mov_b32_e32 v167, v142
	v_mov_b32_e32 v231, v162
	s_waitcnt lgkmcnt(1)
	v_pk_mul_f32 v[160:161], v[140:141], s[0:1] op_sel_hi:[1,0]
	v_pk_mul_f32 v[158:159], v[138:139], s[0:1] op_sel_hi:[1,0]
	s_waitcnt vmcnt(0)
	v_fma_f32 v140, v146, v227, v150
	v_pk_mul_f32 v[138:139], v[166:167], v[230:231]
	v_cvt_f32_i32_e32 v121, v121
	v_add_f32_e32 v139, v139, v140
	v_add_f32_e32 v140, v138, v139
	v_mul_f32_e32 v138, 0x3d372713, v140
	v_mul_f32_e32 v138, v140, v138
	v_fma_f32 v138, v140, v138, v140
	v_mul_f32_e32 v138, 0x3f4c422a, v138
	v_add_f32_e32 v138, v138, v138
	v_cvt_f32_i32_e32 v120, v120
	v_mul_f32_e32 v138, 0xbfb8aa3b, v138
	v_exp_f32_e32 v141, v138
	v_mov_b32_e32 v138, v212
	v_pk_mul_f32 v[120:121], v[160:161], v[120:121]
	v_mov_b32_e32 v139, v212
	v_pk_mul_f32 v[120:121], v[138:139], v[120:121]
	v_add_f32_e32 v138, 1.0, v141
	v_mov_b32_e32 v142, v155
	v_mov_b32_e32 v229, v163
	v_rcp_f32_e32 v141, v138
	v_fma_f32 v154, v147, v225, v151
	v_pk_mul_f32 v[138:139], v[142:143], v[228:229]
	v_cvt_f32_i32_e32 v119, v119
	v_add_f32_e32 v139, v139, v154
	v_add_f32_e32 v154, v138, v139
	v_mul_f32_e32 v138, 0x3d372713, v154
	v_mul_f32_e32 v138, v154, v138
	v_fma_f32 v138, v154, v138, v154
	v_mul_f32_e32 v138, 0x3f4c422a, v138
	v_add_f32_e32 v138, v138, v138
	v_cvt_f32_i32_e32 v118, v118
	v_mul_f32_e32 v138, 0xbfb8aa3b, v138
	v_exp_f32_e32 v138, v138
	v_mov_b32_e32 v213, v212
	v_pk_mul_f32 v[118:119], v[158:159], v[118:119]
	v_mul_f32_e32 v139, v140, v141
	v_pk_mul_f32 v[118:119], v[212:213], v[118:119]
	v_add_f32_e32 v138, 1.0, v138
	v_mov_b32_e32 v162, v156
	v_mov_b32_e32 v163, v144
	v_mov_b32_e32 v227, v164
	v_mul_f32_e32 v118, v118, v139
	v_rcp_f32_e32 v140, v138
	v_fma_f32 v141, v148, v221, v152
	v_pk_mul_f32 v[138:139], v[162:163], v[226:227]
	v_mov_b32_e32 v144, v157
	v_add_f32_e32 v139, v139, v141
	v_add_f32_e32 v141, v138, v139
	v_mul_f32_e32 v138, 0x3d372713, v141
	v_mul_f32_e32 v138, v141, v138
	v_fma_f32 v138, v141, v138, v141
	v_mul_f32_e32 v138, 0x3f4c422a, v138
	v_add_f32_e32 v138, v138, v138
	v_mul_f32_e32 v138, 0xbfb8aa3b, v138
	v_mov_b32_e32 v225, v165
	v_exp_f32_e32 v155, v138
	v_fma_f32 v156, v149, v223, v153
	v_pk_mul_f32 v[138:139], v[144:145], v[224:225]
	v_mul_f32_e32 v140, v154, v140
	v_add_f32_e32 v139, v139, v156
	v_add_f32_e32 v138, v138, v139
	v_mul_f32_e32 v139, 0x3d372713, v138
	v_mul_f32_e32 v139, v138, v139
	v_fma_f32 v139, v138, v139, v138
	v_mul_f32_e32 v139, 0x3f4c422a, v139
	v_add_f32_e32 v139, v139, v139
	v_mul_f32_e32 v139, 0xbfb8aa3b, v139
	v_exp_f32_e32 v139, v139
	v_add_f32_e32 v154, 1.0, v155
	v_rcp_f32_e32 v154, v154
	v_mul_f32_e32 v119, v119, v140
	v_add_f32_e32 v139, 1.0, v139
	v_rcp_f32_e32 v139, v139
	v_mul_f32_e32 v140, v141, v154
	v_mul_f32_e32 v120, v120, v140
	v_cvt_pk_bf16_f32 v118, v118, v119
	v_mul_f32_e32 v138, v138, v139
	v_mul_f32_e32 v121, v121, v138
	v_cvt_pk_bf16_f32 v119, v120, v121
	v_mov_b64_e32 v[120:121], s[24:25]
	v_mad_i64_i32 v[120:121], s[2:3], v200, s83, v[120:121]
	v_mov_b32_e32 v211, v210
	v_mov_b32_e32 v209, v208
	v_mov_b32_e32 v207, v206
	v_mov_b32_e32 v199, v198
	v_mov_b32_e32 v197, v196
	v_mov_b32_e32 v193, v192
	v_mov_b32_e32 v191, v190
	v_lshl_add_u64 v[154:155], v[194:195], 1, v[120:121]
	s_mov_b64 s[2:3], -1
	s_and_b64 vcc, exec, s[62:63]
	global_store_dwordx2 v[154:155], v[118:119], off
	s_cbranch_vccz .LBB0_2614
	v_cndmask_b32_e64 v119, v126, v134, s[16:17]
	v_cndmask_b32_e64 v120, v127, v135, s[16:17]
	s_nop 0
	v_mov_b32_dpp v118, v119 row_ror:1 row_mask:0xf bank_mask:0xf
	v_cndmask_b32_e64 v119, v134, v126, s[38:39]
	v_cndmask_b32_e64 v121, v128, v136, s[16:17]
	s_nop 0
	v_mov_b32_dpp v165, v119 row_ror:2 row_mask:0xf bank_mask:0xf
	v_cndmask_b32_e64 v134, v129, v137, s[16:17]
	v_mov_b32_dpp v119, v120 row_ror:1 row_mask:0xf bank_mask:0xf
	v_cndmask_b32_e64 v120, v135, v127, s[38:39]
	s_mov_b64 s[2:3], 0
	s_nop 0
	v_mov_b32_dpp v157, v120 row_ror:2 row_mask:0xf bank_mask:0xf
	v_mov_b32_e32 v164, v126
	v_mov_b32_e32 v156, v127
	v_mov_b32_dpp v120, v121 row_ror:1 row_mask:0xf bank_mask:0xf
	v_cndmask_b32_e64 v121, v136, v128, s[38:39]
	v_mov_b32_e32 v140, v128
	v_mov_b32_e32 v138, v129
	v_mov_b32_dpp v139, v121 row_ror:2 row_mask:0xf bank_mask:0xf
	s_nop 1
	v_mov_b32_dpp v121, v134 row_ror:1 row_mask:0xf bank_mask:0xf
	v_cndmask_b32_e64 v134, v137, v129, s[38:39]
	s_nop 1
	v_mov_b32_dpp v223, v134 row_ror:2 row_mask:0xf bank_mask:0xf

; __device__ __forceinline__ unsigned cvt_pk_bf16(float lo, float hi) { unsigned r; asm("v_cvt_pk_bf16_f32 %0, %1, %2" : "=v"(r) : "v"(lo), "v"(hi)); return r; }
;     __device__ __forceinline__ void operator()(f32x4 (&acc)[2][2][4][2], const pg8::Unit& u, int wr, int wc, int fr, int fq) const {
;     ...
;                 for (int n = 0; n < 2; ++n) { const u32x4 c = *(const u32x4*)(cmax + u.pn * 256 + bj * 128 + cl0 + 4 * n); sw[bj][n] = (f32x4){__uint_as_float(c.x), __uint_as_float(c.y), __uint_as_float(c.z), __uint_as_float(c.w)} * (1.004f / 127.0f); }
; #pragma unroll
;             for (int ai = 0; ai < 2; ++ai)
; #pragma unroll
;                 for (int m = 0; m < 4; ++m)
; #pragma unroll
;                     for (int bj = 0; bj < 2; ++bj)
; #pragma unroll
;                         for (int n = 0; n < 2; ++n) { const i32x4 q = __builtin_bit_cast(i32x4, acc[ai][bj][m][n]); acc[ai][bj][m][n] = (f32x4){(float)q[0], (float)q[1], (float)q[2], (float)q[3]} * sw[bj][n] * sc[ai][m]; }
;     ...
;                 for (int m = 0; m < 4; ++m) { const int row = row0 + ai * 128 + m * 16; const f32x4 g = acc[ai][0][m][n], vv = acc[ai][1][m][n]; f32x4 p1, p2;
;                     if (prompt) { const f32x4 gp = (m == 0) ? hal[n] : acc[ai][0][m > 0 ? m - 1 : 0][n];
; #pragma unroll
;                         for (int j = 0; j < 4; ++j) { p1[j] = dpp_ror1(fr == 15 ? gp[j] : g[j]); p2[j] = dpp_ror2(fr >= 14 ? gp[j] : g[j]); } }
;                     else { const int t = fr & 3; const float* sp = stf + (size_t)((row - MP) >> 2) * 2 * DFF + ch0 + 4 * n;
;                         f32x4 b0 = (f32x4){0.f, 0.f, 0.f, 0.f}, b1 = b0; if (t == 0) b0 = *(const f32x4*)sp; if (t <= 1) b1 = *(const f32x4*)(sp + DFF);
; #pragma unroll
;                         for (int j = 0; j < 4; ++j) { const float r1 = dpp_ror1(g[j]), r2 = dpp_ror2(g[j]); p1[j] = t >= 1 ? r1 : b1[j]; p2[j] = t >= 2 ? r2 : (t == 1 ? b1[j] : b0[j]); } }
;                     float o[4];
; #pragma unroll
;                     for (int j = 0; j < 4; ++j) { const float y = bb[j] + w0[j] * p2[j] + w1[j] * p1[j] + w2[j] * g[j]; o[j] = gelu_tanh(y) * vv[j]; }
;                     u32x2 w; w.x = cvt_pk_bf16(o[0], o[1]); w.y = cvt_pk_bf16(o[2], o[3]);
;                     *(u32x2*)(ACT + (size_t)row * DFF + ch0 + 4 * n) = w; } } }
.LBB0_2619:
	s_or_b64 exec, exec, s[2:3]
	s_waitcnt vmcnt(0)
	v_cndmask_b32_e64 v120, v134, v138, s[14:15]
	v_cndmask_b32_e64 v121, v135, v139, s[14:15]
	v_mov_b32_dpp v119, v126 row_ror:2 row_mask:0xf bank_mask:0xf
	v_cndmask_b32_e64 v165, v120, v119, s[12:13]
	v_cndmask_b32_e64 v134, v136, v140, s[14:15]
	v_mov_b32_dpp v120, v127 row_ror:2 row_mask:0xf bank_mask:0xf
	v_cndmask_b32_e64 v157, v121, v120, s[12:13]
	v_mov_b32_dpp v119, v127 row_ror:1 row_mask:0xf bank_mask:0xf
	v_mov_b32_dpp v121, v128 row_ror:2 row_mask:0xf bank_mask:0xf
	v_cndmask_b32_e64 v119, v119, v139, s[10:11]
	v_cndmask_b32_e64 v139, v134, v121, s[12:13]
	v_mov_b32_dpp v118, v126 row_ror:1 row_mask:0xf bank_mask:0xf
	v_mov_b32_dpp v120, v128 row_ror:1 row_mask:0xf bank_mask:0xf
	v_mov_b32_dpp v121, v129 row_ror:1 row_mask:0xf bank_mask:0xf
	v_mov_b32_dpp v134, v129 row_ror:2 row_mask:0xf bank_mask:0xf
	v_cndmask_b32_e64 v135, v137, v141, s[14:15]
	v_cndmask_b32_e64 v118, v118, v138, s[10:11]
	v_cndmask_b32_e64 v120, v120, v140, s[10:11]
	v_cndmask_b32_e64 v121, v121, v141, s[10:11]
	v_cndmask_b32_e64 v223, v135, v134, s[12:13]
	v_mov_b32_e32 v164, v126
	v_mov_b32_e32 v156, v127
	v_mov_b32_e32 v140, v128
	v_mov_b32_e32 v138, v129
.LBB0_2620:
	v_fma_f32 v136, v146, v165, v150
	v_mov_b32_e32 v165, v118
	v_pk_mul_f32 v[134:135], v[166:167], v[164:165]
	v_cvt_f32_i32_e32 v113, v113
	v_add_f32_e32 v118, v135, v136
	v_add_f32_e32 v136, v134, v118
	v_mul_f32_e32 v118, 0x3d372713, v136
	v_mul_f32_e32 v118, v136, v118
	v_fma_f32 v118, v136, v118, v136
	v_mul_f32_e32 v118, 0x3f4c422a, v118
	v_add_f32_e32 v118, v118, v118
	v_cvt_f32_i32_e32 v112, v112
	v_mul_f32_e32 v118, 0xbfb8aa3b, v118
	v_exp_f32_e32 v118, v118
	v_mov_b32_e32 v134, v210
	v_pk_mul_f32 v[112:113], v[160:161], v[112:113]
	v_mov_b32_e32 v135, v210
	v_pk_mul_f32 v[112:113], v[134:135], v[112:113]
	v_add_f32_e32 v118, 1.0, v118
	v_fma_f32 v135, v147, v157, v151
	v_mov_b32_e32 v157, v119
	v_rcp_f32_e32 v134, v118
	v_pk_mul_f32 v[118:119], v[142:143], v[156:157]
	v_cvt_f32_i32_e32 v111, v111
	v_add_f32_e32 v119, v119, v135
	v_add_f32_e32 v135, v118, v119
	v_mul_f32_e32 v118, 0x3d372713, v135
	v_mul_f32_e32 v118, v135, v118
	v_fma_f32 v118, v135, v118, v135
	v_mul_f32_e32 v118, 0x3f4c422a, v118
	v_add_f32_e32 v118, v118, v118
	v_cvt_f32_i32_e32 v110, v110
	v_mul_f32_e32 v118, 0xbfb8aa3b, v118
	v_exp_f32_e32 v118, v118
	v_mul_f32_e32 v119, v136, v134
	v_pk_mul_f32 v[110:111], v[158:159], v[110:111]
	v_mov_b32_e32 v141, v120
	v_pk_mul_f32 v[110:111], v[210:211], v[110:111]
	v_add_f32_e32 v118, 1.0, v118
	v_mul_f32_e32 v110, v110, v119
	v_rcp_f32_e32 v134, v118
	v_fma_f32 v136, v148, v139, v152
	v_pk_mul_f32 v[118:119], v[162:163], v[140:141]
	v_mov_b32_e32 v139, v121
	v_add_f32_e32 v119, v119, v136
	v_add_f32_e32 v120, v118, v119
	v_mul_f32_e32 v118, 0x3d372713, v120
	v_mul_f32_e32 v118, v120, v118
	v_fma_f32 v118, v120, v118, v120
	v_mul_f32_e32 v118, 0x3f4c422a, v118
	v_add_f32_e32 v118, v118, v118
	v_mul_f32_e32 v118, 0xbfb8aa3b, v118
	v_exp_f32_e32 v136, v118
	v_fma_f32 v137, v149, v223, v153
	v_pk_mul_f32 v[118:119], v[144:145], v[138:139]
	v_mul_f32_e32 v121, v135, v134
	v_add_f32_e32 v119, v119, v137
	v_add_f32_e32 v118, v118, v119
	v_mul_f32_e32 v119, 0x3d372713, v118
	v_mul_f32_e32 v119, v118, v119
	v_fma_f32 v119, v118, v119, v118
	v_mul_f32_e32 v119, 0x3f4c422a, v119
	v_add_f32_e32 v119, v119, v119
	v_mul_f32_e32 v119, 0xbfb8aa3b, v119
	v_exp_f32_e32 v119, v119
	v_add_f32_e32 v134, 1.0, v136
	v_rcp_f32_e32 v134, v134
	v_mul_f32_e32 v111, v111, v121
	v_add_f32_e32 v119, 1.0, v119
	v_rcp_f32_e32 v119, v119
	v_mul_f32_e32 v120, v120, v134
	v_mul_f32_e32 v112, v112, v120
	v_cvt_pk_bf16_f32 v110, v110, v111
	v_mul_f32_e32 v118, v118, v119
	v_mul_f32_e32 v113, v113, v118
	v_cvt_pk_bf16_f32 v111, v112, v113
	v_mov_b64_e32 v[112:113], s[24:25]
	v_mad_i64_i32 v[112:113], s[2:3], v222, s83, v[112:113]
	v_lshl_add_u64 v[134:135], v[194:195], 1, v[112:113]
	s_mov_b64 s[2:3], -1
	s_and_b64 vcc, exec, s[62:63]
	global_store_dwordx2 v[134:135], v[110:111], off
	s_cbranch_vccz .LBB0_2622
	v_cndmask_b32_e64 v111, v122, v126, s[16:17]
	v_cndmask_b32_e64 v112, v123, v127, s[16:17]
	s_nop 0
	v_mov_b32_dpp v110, v111 row_ror:1 row_mask:0xf bank_mask:0xf
	v_cndmask_b32_e64 v111, v126, v122, s[38:39]
	v_cndmask_b32_e64 v113, v124, v128, s[16:17]
	s_nop 0
	v_mov_b32_dpp v139, v111 row_ror:2 row_mask:0xf bank_mask:0xf
	v_cndmask_b32_e64 v118, v125, v129, s[16:17]
	v_mov_b32_dpp v111, v112 row_ror:1 row_mask:0xf bank_mask:0xf
	v_cndmask_b32_e64 v112, v127, v123, s[38:39]
	s_mov_b64 s[2:3], 0
	s_nop 0
	v_mov_b32_dpp v137, v112 row_ror:2 row_mask:0xf bank_mask:0xf
	v_mov_b32_e32 v138, v122
	v_mov_b32_e32 v136, v123
	v_mov_b32_dpp v112, v113 row_ror:1 row_mask:0xf bank_mask:0xf
	v_cndmask_b32_e64 v113, v128, v124, s[38:39]
	v_mov_b32_e32 v120, v124
	s_nop 0
	v_mov_b32_dpp v119, v113 row_ror:2 row_mask:0xf bank_mask:0xf
	s_nop 1
	v_mov_b32_dpp v113, v118 row_ror:1 row_mask:0xf bank_mask:0xf
	v_cndmask_b32_e64 v118, v129, v125, s[38:39]
	s_nop 1
	v_mov_b32_dpp v140, v118 row_ror:2 row_mask:0xf bank_mask:0xf
	v_mov_b32_e32 v118, v125

; __device__ __forceinline__ unsigned cvt_pk_bf16(float lo, float hi) { unsigned r; asm("v_cvt_pk_bf16_f32 %0, %1, %2" : "=v"(r) : "v"(lo), "v"(hi)); return r; }
;     __device__ __forceinline__ void operator()(f32x4 (&acc)[2][2][4][2], const pg8::Unit& u, int wr, int wc, int fr, int fq) const {
;     ...
;                 for (int n = 0; n < 2; ++n) { const u32x4 c = *(const u32x4*)(cmax + u.pn * 256 + bj * 128 + cl0 + 4 * n); sw[bj][n] = (f32x4){__uint_as_float(c.x), __uint_as_float(c.y), __uint_as_float(c.z), __uint_as_float(c.w)} * (1.004f / 127.0f); }
; #pragma unroll
;             for (int ai = 0; ai < 2; ++ai)
; #pragma unroll
;                 for (int m = 0; m < 4; ++m)
; #pragma unroll
;                     for (int bj = 0; bj < 2; ++bj)
; #pragma unroll
;                         for (int n = 0; n < 2; ++n) { const i32x4 q = __builtin_bit_cast(i32x4, acc[ai][bj][m][n]); acc[ai][bj][m][n] = (f32x4){(float)q[0], (float)q[1], (float)q[2], (float)q[3]} * sw[bj][n] * sc[ai][m]; }
;     ...
;                 for (int m = 0; m < 4; ++m) { const int row = row0 + ai * 128 + m * 16; const f32x4 g = acc[ai][0][m][n], vv = acc[ai][1][m][n]; f32x4 p1, p2;
;                     if (prompt) { const f32x4 gp = (m == 0) ? hal[n] : acc[ai][0][m > 0 ? m - 1 : 0][n];
; #pragma unroll
;                         for (int j = 0; j < 4; ++j) { p1[j] = dpp_ror1(fr == 15 ? gp[j] : g[j]); p2[j] = dpp_ror2(fr >= 14 ? gp[j] : g[j]); } }
;                     else { const int t = fr & 3; const float* sp = stf + (size_t)((row - MP) >> 2) * 2 * DFF + ch0 + 4 * n;
;                         f32x4 b0 = (f32x4){0.f, 0.f, 0.f, 0.f}, b1 = b0; if (t == 0) b0 = *(const f32x4*)sp; if (t <= 1) b1 = *(const f32x4*)(sp + DFF);
; #pragma unroll
;                         for (int j = 0; j < 4; ++j) { const float r1 = dpp_ror1(g[j]), r2 = dpp_ror2(g[j]); p1[j] = t >= 1 ? r1 : b1[j]; p2[j] = t >= 2 ? r2 : (t == 1 ? b1[j] : b0[j]); } }
;                     float o[4];
; #pragma unroll
;                     for (int j = 0; j < 4; ++j) { const float y = bb[j] + w0[j] * p2[j] + w1[j] * p1[j] + w2[j] * g[j]; o[j] = gelu_tanh(y) * vv[j]; }
;                     u32x2 w; w.x = cvt_pk_bf16(o[0], o[1]); w.y = cvt_pk_bf16(o[2], o[3]);
;                     *(u32x2*)(ACT + (size_t)row * DFF + ch0 + 4 * n) = w; } } }
.LBB0_2627:
	s_or_b64 exec, exec, s[2:3]
	s_waitcnt vmcnt(0)
	v_cndmask_b32_e64 v112, v118, v126, s[14:15]
	v_cndmask_b32_e64 v113, v119, v127, s[14:15]
	v_mov_b32_dpp v111, v122 row_ror:2 row_mask:0xf bank_mask:0xf
	v_cndmask_b32_e64 v139, v112, v111, s[12:13]
	v_cndmask_b32_e64 v118, v120, v128, s[14:15]
	v_mov_b32_dpp v112, v123 row_ror:2 row_mask:0xf bank_mask:0xf
	v_cndmask_b32_e64 v137, v113, v112, s[12:13]
	v_mov_b32_dpp v113, v124 row_ror:2 row_mask:0xf bank_mask:0xf
	v_cndmask_b32_e64 v119, v118, v113, s[12:13]
	v_mov_b32_dpp v110, v122 row_ror:1 row_mask:0xf bank_mask:0xf
	v_mov_b32_dpp v111, v123 row_ror:1 row_mask:0xf bank_mask:0xf
	v_mov_b32_dpp v112, v124 row_ror:1 row_mask:0xf bank_mask:0xf
	v_mov_b32_dpp v113, v125 row_ror:1 row_mask:0xf bank_mask:0xf
	v_mov_b32_dpp v118, v125 row_ror:2 row_mask:0xf bank_mask:0xf
	v_cndmask_b32_e64 v120, v121, v129, s[14:15]
	v_cndmask_b32_e64 v110, v110, v126, s[10:11]
	v_cndmask_b32_e64 v111, v111, v127, s[10:11]
	v_cndmask_b32_e64 v112, v112, v128, s[10:11]
	v_cndmask_b32_e64 v113, v113, v129, s[10:11]
	v_cndmask_b32_e64 v140, v120, v118, s[12:13]
	v_mov_b32_e32 v138, v122
	v_mov_b32_e32 v136, v123
	v_mov_b32_e32 v120, v124
	v_mov_b32_e32 v118, v125
.LBB0_2628:
	v_fma_f32 v121, v146, v139, v150
	v_mov_b32_e32 v139, v110
	v_pk_mul_f32 v[126:127], v[166:167], v[138:139]
	v_cvt_f32_i32_e32 v101, v101
	v_add_f32_e32 v110, v127, v121
	v_add_f32_e32 v121, v126, v110
	v_mul_f32_e32 v110, 0x3d372713, v121
	v_mul_f32_e32 v110, v121, v110
	v_fma_f32 v110, v121, v110, v121
	v_mul_f32_e32 v110, 0x3f4c422a, v110
	v_add_f32_e32 v110, v110, v110
	v_cvt_f32_i32_e32 v100, v100
	v_mul_f32_e32 v110, 0xbfb8aa3b, v110
	v_exp_f32_e32 v110, v110
	v_mov_b32_e32 v126, v208
	v_pk_mul_f32 v[100:101], v[160:161], v[100:101]
	v_mov_b32_e32 v127, v208
	v_pk_mul_f32 v[100:101], v[126:127], v[100:101]
	v_add_f32_e32 v110, 1.0, v110
	v_fma_f32 v127, v147, v137, v151
	v_mov_b32_e32 v137, v111
	v_rcp_f32_e32 v126, v110
	v_pk_mul_f32 v[110:111], v[142:143], v[136:137]
	v_cvt_f32_i32_e32 v99, v99
	v_add_f32_e32 v111, v111, v127
	v_add_f32_e32 v127, v110, v111
	v_mul_f32_e32 v110, 0x3d372713, v127
	v_mul_f32_e32 v110, v127, v110
	v_fma_f32 v110, v127, v110, v127
	v_mul_f32_e32 v110, 0x3f4c422a, v110
	v_add_f32_e32 v110, v110, v110
	v_cvt_f32_i32_e32 v98, v98
	v_mul_f32_e32 v110, 0xbfb8aa3b, v110
	v_exp_f32_e32 v110, v110
	v_mul_f32_e32 v111, v121, v126
	v_pk_mul_f32 v[98:99], v[158:159], v[98:99]
	v_mov_b32_e32 v121, v112
	v_pk_mul_f32 v[98:99], v[208:209], v[98:99]
	v_add_f32_e32 v110, 1.0, v110
	v_mul_f32_e32 v98, v98, v111
	v_rcp_f32_e32 v126, v110
	v_fma_f32 v119, v148, v119, v152
	v_pk_mul_f32 v[110:111], v[162:163], v[120:121]
	v_fma_f32 v121, v149, v140, v153
	v_add_f32_e32 v111, v111, v119
	v_add_f32_e32 v112, v110, v111
	v_mul_f32_e32 v110, 0x3d372713, v112
	v_mul_f32_e32 v110, v112, v110
	v_fma_f32 v110, v112, v110, v112
	v_mul_f32_e32 v110, 0x3f4c422a, v110
	v_add_f32_e32 v110, v110, v110
	v_mul_f32_e32 v110, 0xbfb8aa3b, v110
	v_mov_b32_e32 v119, v113
	v_exp_f32_e32 v120, v110
	v_pk_mul_f32 v[110:111], v[144:145], v[118:119]
	v_mul_f32_e32 v113, v127, v126
	v_add_f32_e32 v111, v111, v121
	v_add_f32_e32 v110, v110, v111
	v_mul_f32_e32 v111, 0x3d372713, v110
	v_mul_f32_e32 v111, v110, v111
	v_fma_f32 v111, v110, v111, v110
	v_mul_f32_e32 v111, 0x3f4c422a, v111
	v_add_f32_e32 v111, v111, v111
	v_mul_f32_e32 v111, 0xbfb8aa3b, v111
	v_exp_f32_e32 v111, v111
	v_add_f32_e32 v118, 1.0, v120
	v_rcp_f32_e32 v118, v118
	v_mul_f32_e32 v99, v99, v113
	v_add_f32_e32 v111, 1.0, v111
	v_rcp_f32_e32 v111, v111
	v_mul_f32_e32 v112, v112, v118
	v_mul_f32_e32 v100, v100, v112
	v_cvt_pk_bf16_f32 v98, v98, v99
	v_mul_f32_e32 v110, v110, v111
	v_mul_f32_e32 v101, v101, v110
	v_cvt_pk_bf16_f32 v99, v100, v101
	v_mov_b64_e32 v[100:101], s[24:25]
	v_mad_i64_i32 v[100:101], s[2:3], v220, s83, v[100:101]
	v_lshl_add_u64 v[138:139], v[194:195], 1, v[100:101]
	s_mov_b64 s[2:3], -1
	s_and_b64 vcc, exec, s[62:63]
	global_store_dwordx2 v[138:139], v[98:99], off
	s_cbranch_vccz .LBB0_2630
	v_cndmask_b32_e64 v99, v114, v122, s[16:17]
	v_cndmask_b32_e64 v100, v115, v123, s[16:17]
	s_nop 0
	v_mov_b32_dpp v98, v99 row_ror:1 row_mask:0xf bank_mask:0xf
	v_cndmask_b32_e64 v99, v122, v114, s[38:39]
	v_cndmask_b32_e64 v101, v116, v124, s[16:17]
	s_nop 0
	v_mov_b32_dpp v126, v99 row_ror:2 row_mask:0xf bank_mask:0xf
	v_cndmask_b32_e64 v110, v117, v125, s[16:17]
	v_mov_b32_dpp v99, v100 row_ror:1 row_mask:0xf bank_mask:0xf
	v_cndmask_b32_e64 v100, v123, v115, s[38:39]
	s_mov_b64 s[2:3], 0
	s_nop 0
	v_mov_b32_dpp v119, v100 row_ror:2 row_mask:0xf bank_mask:0xf
	v_mov_b32_e32 v112, v115
	s_nop 0
	v_mov_b32_dpp v100, v101 row_ror:1 row_mask:0xf bank_mask:0xf
	v_cndmask_b32_e64 v101, v124, v116, s[38:39]
	s_nop 1
	v_mov_b32_dpp v111, v101 row_ror:2 row_mask:0xf bank_mask:0xf
	s_nop 1
	v_mov_b32_dpp v101, v110 row_ror:1 row_mask:0xf bank_mask:0xf
	v_cndmask_b32_e64 v110, v125, v117, s[38:39]
	s_nop 1
	v_mov_b32_dpp v118, v110 row_ror:2 row_mask:0xf bank_mask:0xf
	v_mov_b32_e32 v110, v117

;     __device__ __forceinline__ void operator()(f32x4 (&acc)[2][2][4][2], const pg8::Unit& u, int wr, int wc, int fr, int fq) const {
;     ...
;                 for (int n = 0; n < 2; ++n) { const u32x4 c = *(const u32x4*)(cmax + u.pn * 256 + bj * 128 + cl0 + 4 * n); sw[bj][n] = (f32x4){__uint_as_float(c.x), __uint_as_float(c.y), __uint_as_float(c.z), __uint_as_float(c.w)} * (1.004f / 127.0f); }
; #pragma unroll
;             for (int ai = 0; ai < 2; ++ai)
; #pragma unroll
;                 for (int m = 0; m < 4; ++m)
; #pragma unroll
;                     for (int bj = 0; bj < 2; ++bj)
; #pragma unroll
;                         for (int n = 0; n < 2; ++n) { const i32x4 q = __builtin_bit_cast(i32x4, acc[ai][bj][m][n]); acc[ai][bj][m][n] = (f32x4){(float)q[0], (float)q[1], (float)q[2], (float)q[3]} * sw[bj][n] * sc[ai][m]; }
;     ...
;             for (int n = 0; n < 2; ++n) {
;                 const f32x4 w0 = *(const f32x4*)(cw + ch0 + 4 * n), w1 = *(const f32x4*)(cw + DFF + ch0 + 4 * n), w2 = *(const f32x4*)(cw + 2 * DFF + ch0 + 4 * n), bb = *(const f32x4*)(cb + ch0 + 4 * n);
; #pragma unroll
;                 for (int m = 0; m < 4; ++m) { const int row = row0 + ai * 128 + m * 16; const f32x4 g = acc[ai][0][m][n], vv = acc[ai][1][m][n]; f32x4 p1, p2;
;                     if (prompt) { const f32x4 gp = (m == 0) ? hal[n] : acc[ai][0][m > 0 ? m - 1 : 0][n];
; #pragma unroll
;                         for (int j = 0; j < 4; ++j) { p1[j] = dpp_ror1(fr == 15 ? gp[j] : g[j]); p2[j] = dpp_ror2(fr >= 14 ? gp[j] : g[j]); } }
;                     else { const int t = fr & 3; const float* sp = stf + (size_t)((row - MP) >> 2) * 2 * DFF + ch0 + 4 * n;
;                         f32x4 b0 = (f32x4){0.f, 0.f, 0.f, 0.f}, b1 = b0; if (t == 0) b0 = *(const f32x4*)sp; if (t <= 1) b1 = *(const f32x4*)(sp + DFF);
; #pragma unroll
;                         for (int j = 0; j < 4; ++j) { const float r1 = dpp_ror1(g[j]), r2 = dpp_ror2(g[j]); p1[j] = t >= 1 ? r1 : b1[j]; p2[j] = t >= 2 ? r2 : (t == 1 ? b1[j] : b0[j]); } }
;                     float o[4];
; #pragma unroll
;                     for (int j = 0; j < 4; ++j) { const float y = bb[j] + w0[j] * p2[j] + w1[j] * p1[j] + w2[j] * g[j]; o[j] = gelu_tanh(y) * vv[j]; }
;                     u32x2 w; w.x = cvt_pk_bf16(o[0], o[1]); w.y = cvt_pk_bf16(o[2], o[3]);
;                     *(u32x2*)(ACT + (size_t)row * DFF + ch0 + 4 * n) = w; } } }
.LBB0_2635:
	s_or_b64 exec, exec, s[2:3]
	s_waitcnt vmcnt(0)
	v_cndmask_b32_e64 v100, v110, v118, s[14:15]
	v_cndmask_b32_e64 v101, v111, v119, s[14:15]
	v_mov_b32_dpp v99, v114 row_ror:2 row_mask:0xf bank_mask:0xf
	v_cndmask_b32_e64 v126, v100, v99, s[12:13]
	v_cndmask_b32_e64 v110, v112, v120, s[14:15]
	v_mov_b32_dpp v99, v115 row_ror:1 row_mask:0xf bank_mask:0xf
	v_mov_b32_dpp v100, v115 row_ror:2 row_mask:0xf bank_mask:0xf
	v_cndmask_b32_e64 v99, v99, v119, s[10:11]
	v_cndmask_b32_e64 v119, v101, v100, s[12:13]
	v_mov_b32_dpp v101, v116 row_ror:2 row_mask:0xf bank_mask:0xf
	v_cndmask_b32_e64 v111, v110, v101, s[12:13]
	v_mov_b32_dpp v98, v114 row_ror:1 row_mask:0xf bank_mask:0xf
	v_mov_b32_dpp v100, v116 row_ror:1 row_mask:0xf bank_mask:0xf
	v_mov_b32_dpp v101, v117 row_ror:1 row_mask:0xf bank_mask:0xf
	v_mov_b32_dpp v110, v117 row_ror:2 row_mask:0xf bank_mask:0xf
	v_cndmask_b32_e64 v112, v113, v121, s[14:15]
	v_cndmask_b32_e64 v98, v98, v118, s[10:11]
	v_cndmask_b32_e64 v100, v100, v120, s[10:11]
	v_cndmask_b32_e64 v101, v101, v121, s[10:11]
	v_cndmask_b32_e64 v118, v112, v110, s[12:13]
	v_mov_b32_e32 v112, v115
	v_mov_b32_e32 v110, v117
.LBB0_2636:
	v_mov_b32_e32 v115, v98
	v_fma_f32 v113, v146, v126, v150
	v_pk_mul_f32 v[114:115], v[166:167], v[114:115]
	v_cvt_f32_i32_e32 v93, v93
	v_add_f32_e32 v98, v115, v113
	v_add_f32_e32 v117, v114, v98
	v_mul_f32_e32 v98, 0x3d372713, v117
	v_mul_f32_e32 v98, v117, v98
	v_fma_f32 v98, v117, v98, v117
	v_mul_f32_e32 v98, 0x3f4c422a, v98
	v_add_f32_e32 v98, v98, v98
	v_mul_f32_e32 v98, 0xbfb8aa3b, v98
	v_cvt_f32_i32_e32 v92, v92
	v_exp_f32_e32 v98, v98
	v_mov_b32_e32 v114, v206
	v_mov_b32_e32 v115, v206
	v_pk_mul_f32 v[92:93], v[160:161], v[92:93]
	v_add_f32_e32 v98, 1.0, v98
	v_mov_b32_e32 v113, v99
	v_pk_mul_f32 v[92:93], v[114:115], v[92:93]
	v_rcp_f32_e32 v114, v98
	v_fma_f32 v115, v147, v119, v151
	v_pk_mul_f32 v[98:99], v[142:143], v[112:113]
	v_cvt_f32_i32_e32 v91, v91
	v_add_f32_e32 v99, v99, v115
	v_add_f32_e32 v112, v98, v99
	v_mul_f32_e32 v98, 0x3d372713, v112
	v_mul_f32_e32 v98, v112, v98
	v_fma_f32 v98, v112, v98, v112
	v_mul_f32_e32 v98, 0x3f4c422a, v98
	v_add_f32_e32 v98, v98, v98
	v_cvt_f32_i32_e32 v90, v90
	v_mul_f32_e32 v98, 0xbfb8aa3b, v98
	v_exp_f32_e32 v98, v98
	v_mul_f32_e32 v99, v117, v114
	v_pk_mul_f32 v[90:91], v[158:159], v[90:91]
	v_mov_b32_e32 v117, v100
	v_pk_mul_f32 v[90:91], v[206:207], v[90:91]
	v_add_f32_e32 v98, 1.0, v98
	v_mul_f32_e32 v90, v90, v99
	v_rcp_f32_e32 v113, v98
	v_fma_f32 v111, v148, v111, v152
	v_pk_mul_f32 v[98:99], v[162:163], v[116:117]
	v_fmac_f32_e32 v153, v149, v118
	v_add_f32_e32 v99, v99, v111
	v_add_f32_e32 v100, v98, v99
	v_mul_f32_e32 v98, 0x3d372713, v100
	v_mul_f32_e32 v98, v100, v98
	v_fma_f32 v98, v100, v98, v100
	v_mul_f32_e32 v98, 0x3f4c422a, v98
	v_add_f32_e32 v98, v98, v98
	v_mul_f32_e32 v98, 0xbfb8aa3b, v98
	v_mov_b32_e32 v111, v101
	v_exp_f32_e32 v114, v98
	v_pk_mul_f32 v[98:99], v[144:145], v[110:111]
	v_mul_f32_e32 v101, v112, v113
	v_add_f32_e32 v99, v99, v153
	v_add_f32_e32 v98, v98, v99
	v_mul_f32_e32 v99, 0x3d372713, v98
	v_mul_f32_e32 v99, v98, v99
	v_fma_f32 v99, v98, v99, v98
	v_mul_f32_e32 v99, 0x3f4c422a, v99
	v_add_f32_e32 v99, v99, v99
	v_mul_f32_e32 v99, 0xbfb8aa3b, v99
	v_exp_f32_e32 v99, v99
	v_add_f32_e32 v110, 1.0, v114
	v_rcp_f32_e32 v110, v110
	v_mul_f32_e32 v91, v91, v101
	v_add_f32_e32 v99, 1.0, v99
	v_rcp_f32_e32 v99, v99
	v_mul_f32_e32 v100, v100, v110
	v_mul_f32_e32 v92, v92, v100
	v_cvt_pk_bf16_f32 v90, v90, v91
	v_mul_f32_e32 v98, v98, v99
	v_mul_f32_e32 v93, v93, v98
	v_cvt_pk_bf16_f32 v91, v92, v93
	v_mov_b64_e32 v[92:93], s[24:25]
	v_add_co_u32_e32 v98, vcc, 0xc000, v202
	v_mad_i64_i32 v[92:93], s[2:3], v218, s83, v[92:93]
	s_nop 0
	v_addc_co_u32_e32 v99, vcc, 0, v203, vcc
	v_lshl_add_u64 v[136:137], v[194:195], 1, v[92:93]
	v_add_co_u32_e32 v110, vcc, 0x18000, v202
	global_store_dwordx2 v[136:137], v[90:91], off
	s_nop 0
	v_addc_co_u32_e32 v111, vcc, 0, v203, vcc
	global_load_dwordx4 v[90:93], v[202:203], off offset:16
	s_nop 0
	global_load_dwordx4 v[98:101], v[98:99], off offset:16
	s_nop 0
	global_load_dwordx4 v[114:117], v[110:111], off offset:16
	s_nop 0
	global_load_dwordx4 v[110:113], v[204:205], off offset:16
	s_mov_b64 s[2:3], -1
	s_and_b64 vcc, exec, s[62:63]
	s_cbranch_vccz .LBB0_2638
	s_waitcnt lgkmcnt(0)
	v_cndmask_b32_e64 v119, v102, v130, s[16:17]
	v_cndmask_b32_e64 v120, v103, v131, s[16:17]
	s_nop 0
	v_mov_b32_dpp v118, v119 row_ror:1 row_mask:0xf bank_mask:0xf
	v_cndmask_b32_e64 v119, v130, v102, s[38:39]
	v_cndmask_b32_e64 v121, v104, v132, s[16:17]
	s_nop 0
	v_mov_b32_dpp v145, v119 row_ror:2 row_mask:0xf bank_mask:0xf
	v_cndmask_b32_e64 v122, v105, v133, s[16:17]
	v_mov_b32_dpp v119, v120 row_ror:1 row_mask:0xf bank_mask:0xf
	v_cndmask_b32_e64 v120, v131, v103, s[38:39]
	s_mov_b64 s[2:3], 0
	s_nop 0
	v_mov_b32_dpp v143, v120 row_ror:2 row_mask:0xf bank_mask:0xf
	v_mov_b32_e32 v146, v102
	v_mov_b32_e32 v144, v103
	v_mov_b32_dpp v120, v121 row_ror:1 row_mask:0xf bank_mask:0xf
	v_cndmask_b32_e64 v121, v132, v104, s[38:39]
	v_mov_b32_e32 v142, v104
	v_mov_b32_e32 v140, v105
	v_mov_b32_dpp v141, v121 row_ror:2 row_mask:0xf bank_mask:0xf
	s_nop 1
	v_mov_b32_dpp v121, v122 row_ror:1 row_mask:0xf bank_mask:0xf
	v_cndmask_b32_e64 v122, v133, v105, s[38:39]
	s_nop 1
	v_mov_b32_dpp v148, v122 row_ror:2 row_mask:0xf bank_mask:0xf

; __device__ __forceinline__ unsigned cvt_pk_bf16(float lo, float hi) { unsigned r; asm("v_cvt_pk_bf16_f32 %0, %1, %2" : "=v"(r) : "v"(lo), "v"(hi)); return r; }
;     __device__ __forceinline__ void operator()(f32x4 (&acc)[2][2][4][2], const pg8::Unit& u, int wr, int wc, int fr, int fq) const {
;     ...
;                 for (int n = 0; n < 2; ++n) { const u32x4 c = *(const u32x4*)(cmax + u.pn * 256 + bj * 128 + cl0 + 4 * n); sw[bj][n] = (f32x4){__uint_as_float(c.x), __uint_as_float(c.y), __uint_as_float(c.z), __uint_as_float(c.w)} * (1.004f / 127.0f); }
; #pragma unroll
;             for (int ai = 0; ai < 2; ++ai)
; #pragma unroll
;                 for (int m = 0; m < 4; ++m)
; #pragma unroll
;                     for (int bj = 0; bj < 2; ++bj)
; #pragma unroll
;                         for (int n = 0; n < 2; ++n) { const i32x4 q = __builtin_bit_cast(i32x4, acc[ai][bj][m][n]); acc[ai][bj][m][n] = (f32x4){(float)q[0], (float)q[1], (float)q[2], (float)q[3]} * sw[bj][n] * sc[ai][m]; }
;     ...
;                 for (int m = 0; m < 4; ++m) { const int row = row0 + ai * 128 + m * 16; const f32x4 g = acc[ai][0][m][n], vv = acc[ai][1][m][n]; f32x4 p1, p2;
;                     if (prompt) { const f32x4 gp = (m == 0) ? hal[n] : acc[ai][0][m > 0 ? m - 1 : 0][n];
; #pragma unroll
;                         for (int j = 0; j < 4; ++j) { p1[j] = dpp_ror1(fr == 15 ? gp[j] : g[j]); p2[j] = dpp_ror2(fr >= 14 ? gp[j] : g[j]); } }
;                     else { const int t = fr & 3; const float* sp = stf + (size_t)((row - MP) >> 2) * 2 * DFF + ch0 + 4 * n;
;                         f32x4 b0 = (f32x4){0.f, 0.f, 0.f, 0.f}, b1 = b0; if (t == 0) b0 = *(const f32x4*)sp; if (t <= 1) b1 = *(const f32x4*)(sp + DFF);
; #pragma unroll
;                         for (int j = 0; j < 4; ++j) { const float r1 = dpp_ror1(g[j]), r2 = dpp_ror2(g[j]); p1[j] = t >= 1 ? r1 : b1[j]; p2[j] = t >= 2 ? r2 : (t == 1 ? b1[j] : b0[j]); } }
;                     float o[4];
; #pragma unroll
;                     for (int j = 0; j < 4; ++j) { const float y = bb[j] + w0[j] * p2[j] + w1[j] * p1[j] + w2[j] * g[j]; o[j] = gelu_tanh(y) * vv[j]; }
;                     u32x2 w; w.x = cvt_pk_bf16(o[0], o[1]); w.y = cvt_pk_bf16(o[2], o[3]);
;                     *(u32x2*)(ACT + (size_t)row * DFF + ch0 + 4 * n) = w; } } }
.LBB0_2643:
	s_or_b64 exec, exec, s[2:3]
	s_waitcnt vmcnt(0)
	v_cndmask_b32_e64 v120, v120, v124, s[14:15]
	v_cndmask_b32_e64 v121, v121, v125, s[14:15]
	v_mov_b32_dpp v119, v102 row_ror:2 row_mask:0xf bank_mask:0xf
	v_cndmask_b32_e64 v145, v120, v119, s[12:13]
	v_cndmask_b32_e64 v122, v122, v126, s[14:15]
	v_mov_b32_dpp v120, v103 row_ror:2 row_mask:0xf bank_mask:0xf
	v_cndmask_b32_e64 v143, v121, v120, s[12:13]
	v_mov_b32_dpp v121, v104 row_ror:2 row_mask:0xf bank_mask:0xf
	v_cndmask_b32_e64 v141, v122, v121, s[12:13]
	v_mov_b32_dpp v118, v102 row_ror:1 row_mask:0xf bank_mask:0xf
	v_mov_b32_dpp v119, v103 row_ror:1 row_mask:0xf bank_mask:0xf
	v_mov_b32_dpp v120, v104 row_ror:1 row_mask:0xf bank_mask:0xf
	v_mov_b32_dpp v121, v105 row_ror:1 row_mask:0xf bank_mask:0xf
	v_mov_b32_dpp v122, v105 row_ror:2 row_mask:0xf bank_mask:0xf
	v_cndmask_b32_e64 v123, v123, v127, s[14:15]
	v_cndmask_b32_e64 v118, v118, v124, s[10:11]
	v_cndmask_b32_e64 v119, v119, v125, s[10:11]
	v_cndmask_b32_e64 v120, v120, v126, s[10:11]
	v_cndmask_b32_e64 v121, v121, v127, s[10:11]
	v_cndmask_b32_e64 v148, v123, v122, s[12:13]
	v_mov_b32_e32 v146, v102
	v_mov_b32_e32 v144, v103
	v_mov_b32_e32 v142, v104
	v_mov_b32_e32 v140, v105
.LBB0_2644:
	s_waitcnt vmcnt(1) lgkmcnt(0)
	v_mov_b32_e32 v130, v114
	v_mov_b32_e32 v131, v98
	v_mov_b32_e32 v147, v118
	v_pk_mul_f32 v[124:125], v[108:109], s[0:1] op_sel_hi:[1,0]
	v_pk_mul_f32 v[122:123], v[106:107], s[0:1] op_sel_hi:[1,0]
	s_waitcnt vmcnt(0)
	v_fma_f32 v108, v90, v145, v110
	v_pk_mul_f32 v[106:107], v[130:131], v[146:147]
	v_cvt_f32_i32_e32 v85, v85
	v_add_f32_e32 v98, v107, v108
	v_add_f32_e32 v108, v106, v98
	v_mul_f32_e32 v98, 0x3d372713, v108
	v_mul_f32_e32 v98, v108, v98
	v_fma_f32 v98, v108, v98, v108
	v_mul_f32_e32 v98, 0x3f4c422a, v98
	v_add_f32_e32 v98, v98, v98
	v_mul_f32_e32 v98, 0xbfb8aa3b, v98
	v_exp_f32_e32 v98, v98
	v_cvt_f32_i32_e32 v84, v84
	v_mov_b32_e32 v106, v212
	v_mov_b32_e32 v107, v212
	v_add_f32_e32 v98, 1.0, v98
	v_pk_mul_f32 v[84:85], v[124:125], v[84:85]
	v_rcp_f32_e32 v109, v98
	v_mov_b32_e32 v98, v115
	v_mov_b32_e32 v145, v119
	v_pk_mul_f32 v[84:85], v[106:107], v[84:85]
	v_fma_f32 v114, v91, v143, v111
	v_pk_mul_f32 v[106:107], v[98:99], v[144:145]
	v_cvt_f32_i32_e32 v83, v83
	v_add_f32_e32 v107, v107, v114
	v_add_f32_e32 v118, v106, v107
	v_mul_f32_e32 v106, 0x3d372713, v118
	v_mul_f32_e32 v106, v118, v106
	v_fma_f32 v106, v118, v106, v118
	v_mul_f32_e32 v106, 0x3f4c422a, v106
	v_add_f32_e32 v106, v106, v106
	v_cvt_f32_i32_e32 v82, v82
	v_mul_f32_e32 v106, 0xbfb8aa3b, v106
	v_exp_f32_e32 v106, v106
	v_mul_f32_e32 v107, v108, v109
	v_pk_mul_f32 v[82:83], v[122:123], v[82:83]
	v_mov_b32_e32 v114, v116
	v_pk_mul_f32 v[82:83], v[212:213], v[82:83]
	v_add_f32_e32 v106, 1.0, v106
	v_mov_b32_e32 v115, v100
	v_mov_b32_e32 v143, v120
	v_mul_f32_e32 v82, v82, v107
	v_rcp_f32_e32 v108, v106
	v_fma_f32 v109, v92, v141, v112
	v_pk_mul_f32 v[106:107], v[114:115], v[142:143]
	v_mov_b32_e32 v141, v121
	v_add_f32_e32 v100, v107, v109
	v_add_f32_e32 v109, v106, v100
	v_mul_f32_e32 v100, 0x3d372713, v109
	v_mul_f32_e32 v100, v109, v100
	v_fma_f32 v100, v109, v100, v109
	v_mul_f32_e32 v100, 0x3f4c422a, v100
	v_add_f32_e32 v100, v100, v100
	v_mul_f32_e32 v100, 0xbfb8aa3b, v100
	v_exp_f32_e32 v116, v100
	v_mov_b32_e32 v100, v117
	v_fma_f32 v119, v93, v148, v113
	v_pk_mul_f32 v[106:107], v[100:101], v[140:141]
	v_add_f32_e32 v116, 1.0, v116
	v_add_f32_e32 v107, v107, v119
	v_add_f32_e32 v106, v106, v107
	v_mul_f32_e32 v107, 0x3d372713, v106
	v_mul_f32_e32 v107, v106, v107
	v_fma_f32 v107, v106, v107, v106
	v_mul_f32_e32 v107, 0x3f4c422a, v107
	v_add_f32_e32 v107, v107, v107
	v_mul_f32_e32 v107, 0xbfb8aa3b, v107
	v_exp_f32_e32 v107, v107
	v_rcp_f32_e32 v116, v116
	s_mov_b64 s[2:3], 0xc010
	v_mul_f32_e32 v108, v118, v108
	v_add_f32_e32 v107, 1.0, v107
	v_rcp_f32_e32 v107, v107
	v_lshl_add_u64 v[126:127], v[202:203], 0, s[2:3]
	s_mov_b64 s[2:3], 0x18010
	v_mul_f32_e32 v83, v83, v108
	v_mul_f32_e32 v108, v109, v116
	v_mul_f32_e32 v106, v106, v107
	v_lshl_add_u64 v[128:129], v[202:203], 0, s[2:3]
	v_mul_f32_e32 v84, v84, v108
	v_mul_f32_e32 v85, v85, v106
	v_cvt_pk_bf16_f32 v82, v82, v83
	v_cvt_pk_bf16_f32 v83, v84, v85
	s_mov_b64 s[2:3], -1
	s_and_b64 vcc, exec, s[62:63]
	global_store_dwordx2 v[154:155], v[82:83], off offset:8
	s_cbranch_vccz .LBB0_2646
	v_cndmask_b32_e64 v83, v94, v102, s[16:17]
	v_cndmask_b32_e64 v84, v95, v103, s[16:17]
	s_nop 0
	v_mov_b32_dpp v82, v83 row_ror:1 row_mask:0xf bank_mask:0xf
	v_cndmask_b32_e64 v83, v102, v94, s[38:39]
	v_cndmask_b32_e64 v85, v96, v104, s[16:17]
	s_nop 0
	v_mov_b32_dpp v119, v83 row_ror:2 row_mask:0xf bank_mask:0xf
	v_cndmask_b32_e64 v102, v97, v105, s[16:17]
	v_mov_b32_dpp v83, v84 row_ror:1 row_mask:0xf bank_mask:0xf
	v_cndmask_b32_e64 v84, v103, v95, s[38:39]
	s_mov_b64 s[2:3], 0
	s_nop 0
	v_mov_b32_dpp v117, v84 row_ror:2 row_mask:0xf bank_mask:0xf
	v_mov_b32_e32 v118, v94
	v_mov_b32_e32 v116, v95
	v_mov_b32_dpp v84, v85 row_ror:1 row_mask:0xf bank_mask:0xf
	v_cndmask_b32_e64 v85, v104, v96, s[38:39]
	v_mov_b32_e32 v108, v96
	v_mov_b32_e32 v106, v97
	v_mov_b32_dpp v107, v85 row_ror:2 row_mask:0xf bank_mask:0xf
	s_nop 1
	v_mov_b32_dpp v85, v102 row_ror:1 row_mask:0xf bank_mask:0xf
	v_cndmask_b32_e64 v102, v105, v97, s[38:39]
	s_nop 1
	v_mov_b32_dpp v120, v102 row_ror:2 row_mask:0xf bank_mask:0xf

; __device__ __forceinline__ unsigned cvt_pk_bf16(float lo, float hi) { unsigned r; asm("v_cvt_pk_bf16_f32 %0, %1, %2" : "=v"(r) : "v"(lo), "v"(hi)); return r; }
;     __device__ __forceinline__ void operator()(f32x4 (&acc)[2][2][4][2], const pg8::Unit& u, int wr, int wc, int fr, int fq) const {
;     ...
;                 for (int n = 0; n < 2; ++n) { const u32x4 c = *(const u32x4*)(cmax + u.pn * 256 + bj * 128 + cl0 + 4 * n); sw[bj][n] = (f32x4){__uint_as_float(c.x), __uint_as_float(c.y), __uint_as_float(c.z), __uint_as_float(c.w)} * (1.004f / 127.0f); }
; #pragma unroll
;             for (int ai = 0; ai < 2; ++ai)
; #pragma unroll
;                 for (int m = 0; m < 4; ++m)
; #pragma unroll
;                     for (int bj = 0; bj < 2; ++bj)
; #pragma unroll
;                         for (int n = 0; n < 2; ++n) { const i32x4 q = __builtin_bit_cast(i32x4, acc[ai][bj][m][n]); acc[ai][bj][m][n] = (f32x4){(float)q[0], (float)q[1], (float)q[2], (float)q[3]} * sw[bj][n] * sc[ai][m]; }
;     ...
;                 for (int m = 0; m < 4; ++m) { const int row = row0 + ai * 128 + m * 16; const f32x4 g = acc[ai][0][m][n], vv = acc[ai][1][m][n]; f32x4 p1, p2;
;                     if (prompt) { const f32x4 gp = (m == 0) ? hal[n] : acc[ai][0][m > 0 ? m - 1 : 0][n];
; #pragma unroll
;                         for (int j = 0; j < 4; ++j) { p1[j] = dpp_ror1(fr == 15 ? gp[j] : g[j]); p2[j] = dpp_ror2(fr >= 14 ? gp[j] : g[j]); } }
;                     else { const int t = fr & 3; const float* sp = stf + (size_t)((row - MP) >> 2) * 2 * DFF + ch0 + 4 * n;
;                         f32x4 b0 = (f32x4){0.f, 0.f, 0.f, 0.f}, b1 = b0; if (t == 0) b0 = *(const f32x4*)sp; if (t <= 1) b1 = *(const f32x4*)(sp + DFF);
; #pragma unroll
;                         for (int j = 0; j < 4; ++j) { const float r1 = dpp_ror1(g[j]), r2 = dpp_ror2(g[j]); p1[j] = t >= 1 ? r1 : b1[j]; p2[j] = t >= 2 ? r2 : (t == 1 ? b1[j] : b0[j]); } }
;                     float o[4];
; #pragma unroll
;                     for (int j = 0; j < 4; ++j) { const float y = bb[j] + w0[j] * p2[j] + w1[j] * p1[j] + w2[j] * g[j]; o[j] = gelu_tanh(y) * vv[j]; }
;                     u32x2 w; w.x = cvt_pk_bf16(o[0], o[1]); w.y = cvt_pk_bf16(o[2], o[3]);
;                     *(u32x2*)(ACT + (size_t)row * DFF + ch0 + 4 * n) = w; } } }
.LBB0_2651:
	s_or_b64 exec, exec, s[2:3]
	s_waitcnt vmcnt(0)
	v_cndmask_b32_e64 v84, v102, v106, s[14:15]
	v_cndmask_b32_e64 v85, v103, v107, s[14:15]
	v_mov_b32_dpp v83, v94 row_ror:2 row_mask:0xf bank_mask:0xf
	v_cndmask_b32_e64 v119, v84, v83, s[12:13]
	v_cndmask_b32_e64 v102, v104, v108, s[14:15]
	v_mov_b32_dpp v84, v95 row_ror:2 row_mask:0xf bank_mask:0xf
	v_cndmask_b32_e64 v117, v85, v84, s[12:13]
	v_mov_b32_dpp v83, v95 row_ror:1 row_mask:0xf bank_mask:0xf
	v_mov_b32_dpp v85, v96 row_ror:2 row_mask:0xf bank_mask:0xf
	v_cndmask_b32_e64 v83, v83, v107, s[10:11]
	v_cndmask_b32_e64 v107, v102, v85, s[12:13]
	v_mov_b32_dpp v82, v94 row_ror:1 row_mask:0xf bank_mask:0xf
	v_mov_b32_dpp v84, v96 row_ror:1 row_mask:0xf bank_mask:0xf
	v_mov_b32_dpp v85, v97 row_ror:1 row_mask:0xf bank_mask:0xf
	v_mov_b32_dpp v102, v97 row_ror:2 row_mask:0xf bank_mask:0xf
	v_cndmask_b32_e64 v103, v105, v109, s[14:15]
	v_cndmask_b32_e64 v82, v82, v106, s[10:11]
	v_cndmask_b32_e64 v84, v84, v108, s[10:11]
	v_cndmask_b32_e64 v85, v85, v109, s[10:11]
	v_cndmask_b32_e64 v120, v103, v102, s[12:13]
	v_mov_b32_e32 v118, v94
	v_mov_b32_e32 v116, v95
	v_mov_b32_e32 v108, v96
	v_mov_b32_e32 v106, v97
.LBB0_2652:
	v_fma_f32 v104, v90, v119, v110
	v_mov_b32_e32 v119, v82
	v_pk_mul_f32 v[102:103], v[130:131], v[118:119]
	v_cvt_f32_i32_e32 v77, v77
	v_add_f32_e32 v82, v103, v104
	v_add_f32_e32 v104, v102, v82
	v_mul_f32_e32 v82, 0x3d372713, v104
	v_mul_f32_e32 v82, v104, v82
	v_fma_f32 v82, v104, v82, v104
	v_mul_f32_e32 v82, 0x3f4c422a, v82
	v_add_f32_e32 v82, v82, v82
	v_cvt_f32_i32_e32 v76, v76
	v_mul_f32_e32 v82, 0xbfb8aa3b, v82
	v_exp_f32_e32 v82, v82
	v_mov_b32_e32 v102, v210
	v_pk_mul_f32 v[76:77], v[124:125], v[76:77]
	v_mov_b32_e32 v103, v210
	v_pk_mul_f32 v[76:77], v[102:103], v[76:77]
	v_add_f32_e32 v82, 1.0, v82
	v_fma_f32 v103, v91, v117, v111
	v_mov_b32_e32 v117, v83
	v_rcp_f32_e32 v102, v82
	v_pk_mul_f32 v[82:83], v[98:99], v[116:117]
	v_cvt_f32_i32_e32 v75, v75
	v_add_f32_e32 v83, v83, v103
	v_add_f32_e32 v103, v82, v83
	v_mul_f32_e32 v82, 0x3d372713, v103
	v_mul_f32_e32 v82, v103, v82
	v_fma_f32 v82, v103, v82, v103
	v_mul_f32_e32 v82, 0x3f4c422a, v82
	v_add_f32_e32 v82, v82, v82
	v_cvt_f32_i32_e32 v74, v74
	v_mul_f32_e32 v82, 0xbfb8aa3b, v82
	v_exp_f32_e32 v82, v82
	v_mul_f32_e32 v83, v104, v102
	v_pk_mul_f32 v[74:75], v[122:123], v[74:75]
	v_mov_b32_e32 v109, v84
	v_pk_mul_f32 v[74:75], v[210:211], v[74:75]
	v_add_f32_e32 v82, 1.0, v82
	v_mul_f32_e32 v74, v74, v83
	v_rcp_f32_e32 v102, v82
	v_fma_f32 v104, v92, v107, v112
	v_pk_mul_f32 v[82:83], v[114:115], v[108:109]
	v_mov_b32_e32 v107, v85
	v_add_f32_e32 v83, v83, v104
	v_add_f32_e32 v84, v82, v83
	v_mul_f32_e32 v82, 0x3d372713, v84
	v_mul_f32_e32 v82, v84, v82
	v_fma_f32 v82, v84, v82, v84
	v_mul_f32_e32 v82, 0x3f4c422a, v82
	v_add_f32_e32 v82, v82, v82
	v_mul_f32_e32 v82, 0xbfb8aa3b, v82
	v_exp_f32_e32 v104, v82
	v_fma_f32 v105, v93, v120, v113
	v_pk_mul_f32 v[82:83], v[100:101], v[106:107]
	v_mul_f32_e32 v85, v103, v102
	v_add_f32_e32 v83, v83, v105
	v_add_f32_e32 v82, v82, v83
	v_mul_f32_e32 v83, 0x3d372713, v82
	v_mul_f32_e32 v83, v82, v83
	v_fma_f32 v83, v82, v83, v82
	v_mul_f32_e32 v83, 0x3f4c422a, v83
	v_add_f32_e32 v83, v83, v83
	v_mul_f32_e32 v83, 0xbfb8aa3b, v83
	v_exp_f32_e32 v83, v83
	v_add_f32_e32 v102, 1.0, v104
	v_rcp_f32_e32 v102, v102
	v_mul_f32_e32 v75, v75, v85
	v_add_f32_e32 v83, 1.0, v83
	v_rcp_f32_e32 v83, v83
	v_mul_f32_e32 v84, v84, v102
	v_mul_f32_e32 v76, v76, v84
	v_cvt_pk_bf16_f32 v74, v74, v75
	v_mul_f32_e32 v82, v82, v83
	v_mul_f32_e32 v77, v77, v82
	v_cvt_pk_bf16_f32 v75, v76, v77
	s_mov_b64 s[2:3], -1
	s_and_b64 vcc, exec, s[62:63]
	global_store_dwordx2 v[134:135], v[74:75], off offset:8
	s_cbranch_vccz .LBB0_2654
	v_cndmask_b32_e64 v75, v86, v94, s[16:17]
	v_cndmask_b32_e64 v76, v87, v95, s[16:17]
	s_nop 0
	v_mov_b32_dpp v74, v75 row_ror:1 row_mask:0xf bank_mask:0xf
	v_cndmask_b32_e64 v75, v94, v86, s[38:39]
	v_cndmask_b32_e64 v77, v88, v96, s[16:17]
	s_nop 0
	v_mov_b32_dpp v105, v75 row_ror:2 row_mask:0xf bank_mask:0xf
	v_cndmask_b32_e64 v82, v89, v97, s[16:17]
	v_mov_b32_dpp v75, v76 row_ror:1 row_mask:0xf bank_mask:0xf
	v_cndmask_b32_e64 v76, v95, v87, s[38:39]
	s_mov_b64 s[2:3], 0
	s_nop 0
	v_mov_b32_dpp v103, v76 row_ror:2 row_mask:0xf bank_mask:0xf
	v_mov_b32_e32 v104, v86
	v_mov_b32_e32 v102, v87
	v_mov_b32_dpp v76, v77 row_ror:1 row_mask:0xf bank_mask:0xf
	v_cndmask_b32_e64 v77, v96, v88, s[38:39]
	v_mov_b32_e32 v84, v88
	s_nop 0
	v_mov_b32_dpp v83, v77 row_ror:2 row_mask:0xf bank_mask:0xf
	s_nop 1
	v_mov_b32_dpp v77, v82 row_ror:1 row_mask:0xf bank_mask:0xf
	v_cndmask_b32_e64 v82, v97, v89, s[38:39]
	s_nop 1
	v_mov_b32_dpp v106, v82 row_ror:2 row_mask:0xf bank_mask:0xf
	v_mov_b32_e32 v82, v89

; __device__ __forceinline__ unsigned cvt_pk_bf16(float lo, float hi) { unsigned r; asm("v_cvt_pk_bf16_f32 %0, %1, %2" : "=v"(r) : "v"(lo), "v"(hi)); return r; }
;     __device__ __forceinline__ void operator()(f32x4 (&acc)[2][2][4][2], const pg8::Unit& u, int wr, int wc, int fr, int fq) const {
;     ...
;                 for (int n = 0; n < 2; ++n) { const u32x4 c = *(const u32x4*)(cmax + u.pn * 256 + bj * 128 + cl0 + 4 * n); sw[bj][n] = (f32x4){__uint_as_float(c.x), __uint_as_float(c.y), __uint_as_float(c.z), __uint_as_float(c.w)} * (1.004f / 127.0f); }
; #pragma unroll
;             for (int ai = 0; ai < 2; ++ai)
; #pragma unroll
;                 for (int m = 0; m < 4; ++m)
; #pragma unroll
;                     for (int bj = 0; bj < 2; ++bj)
; #pragma unroll
;                         for (int n = 0; n < 2; ++n) { const i32x4 q = __builtin_bit_cast(i32x4, acc[ai][bj][m][n]); acc[ai][bj][m][n] = (f32x4){(float)q[0], (float)q[1], (float)q[2], (float)q[3]} * sw[bj][n] * sc[ai][m]; }
;     ...
;                 for (int m = 0; m < 4; ++m) { const int row = row0 + ai * 128 + m * 16; const f32x4 g = acc[ai][0][m][n], vv = acc[ai][1][m][n]; f32x4 p1, p2;
;                     if (prompt) { const f32x4 gp = (m == 0) ? hal[n] : acc[ai][0][m > 0 ? m - 1 : 0][n];
; #pragma unroll
;                         for (int j = 0; j < 4; ++j) { p1[j] = dpp_ror1(fr == 15 ? gp[j] : g[j]); p2[j] = dpp_ror2(fr >= 14 ? gp[j] : g[j]); } }
;                     else { const int t = fr & 3; const float* sp = stf + (size_t)((row - MP) >> 2) * 2 * DFF + ch0 + 4 * n;
;                         f32x4 b0 = (f32x4){0.f, 0.f, 0.f, 0.f}, b1 = b0; if (t == 0) b0 = *(const f32x4*)sp; if (t <= 1) b1 = *(const f32x4*)(sp + DFF);
; #pragma unroll
;                         for (int j = 0; j < 4; ++j) { const float r1 = dpp_ror1(g[j]), r2 = dpp_ror2(g[j]); p1[j] = t >= 1 ? r1 : b1[j]; p2[j] = t >= 2 ? r2 : (t == 1 ? b1[j] : b0[j]); } }
;                     float o[4];
; #pragma unroll
;                     for (int j = 0; j < 4; ++j) { const float y = bb[j] + w0[j] * p2[j] + w1[j] * p1[j] + w2[j] * g[j]; o[j] = gelu_tanh(y) * vv[j]; }
;                     u32x2 w; w.x = cvt_pk_bf16(o[0], o[1]); w.y = cvt_pk_bf16(o[2], o[3]);
;                     *(u32x2*)(ACT + (size_t)row * DFF + ch0 + 4 * n) = w; } } }
.LBB0_2659:
	s_or_b64 exec, exec, s[2:3]
	s_waitcnt vmcnt(0)
	v_cndmask_b32_e64 v76, v82, v94, s[14:15]
	v_cndmask_b32_e64 v77, v83, v95, s[14:15]
	v_mov_b32_dpp v75, v86 row_ror:2 row_mask:0xf bank_mask:0xf
	v_cndmask_b32_e64 v105, v76, v75, s[12:13]
	v_cndmask_b32_e64 v82, v84, v96, s[14:15]
	v_mov_b32_dpp v76, v87 row_ror:2 row_mask:0xf bank_mask:0xf
	v_cndmask_b32_e64 v103, v77, v76, s[12:13]
	v_mov_b32_dpp v77, v88 row_ror:2 row_mask:0xf bank_mask:0xf
	v_cndmask_b32_e64 v83, v82, v77, s[12:13]
	v_mov_b32_dpp v74, v86 row_ror:1 row_mask:0xf bank_mask:0xf
	v_mov_b32_dpp v75, v87 row_ror:1 row_mask:0xf bank_mask:0xf
	v_mov_b32_dpp v76, v88 row_ror:1 row_mask:0xf bank_mask:0xf
	v_mov_b32_dpp v77, v89 row_ror:1 row_mask:0xf bank_mask:0xf
	v_mov_b32_dpp v82, v89 row_ror:2 row_mask:0xf bank_mask:0xf
	v_cndmask_b32_e64 v84, v85, v97, s[14:15]
	v_cndmask_b32_e64 v74, v74, v94, s[10:11]
	v_cndmask_b32_e64 v75, v75, v95, s[10:11]
	v_cndmask_b32_e64 v76, v76, v96, s[10:11]
	v_cndmask_b32_e64 v77, v77, v97, s[10:11]
	v_cndmask_b32_e64 v106, v84, v82, s[12:13]
	v_mov_b32_e32 v104, v86
	v_mov_b32_e32 v102, v87
	v_mov_b32_e32 v84, v88
	v_mov_b32_e32 v82, v89
.LBB0_2660:
	v_fma_f32 v85, v90, v105, v110
	v_mov_b32_e32 v105, v74
	v_pk_mul_f32 v[94:95], v[130:131], v[104:105]
	v_cvt_f32_i32_e32 v69, v69
	v_add_f32_e32 v74, v95, v85
	v_add_f32_e32 v85, v94, v74
	v_mul_f32_e32 v74, 0x3d372713, v85
	v_mul_f32_e32 v74, v85, v74
	v_fma_f32 v74, v85, v74, v85
	v_mul_f32_e32 v74, 0x3f4c422a, v74
	v_add_f32_e32 v74, v74, v74
	v_cvt_f32_i32_e32 v68, v68
	v_mul_f32_e32 v74, 0xbfb8aa3b, v74
	v_exp_f32_e32 v74, v74
	v_mov_b32_e32 v94, v208
	v_pk_mul_f32 v[68:69], v[124:125], v[68:69]
	v_mov_b32_e32 v95, v208
	v_pk_mul_f32 v[68:69], v[94:95], v[68:69]
	v_add_f32_e32 v74, 1.0, v74
	v_fma_f32 v95, v91, v103, v111
	v_mov_b32_e32 v103, v75
	v_rcp_f32_e32 v94, v74
	v_pk_mul_f32 v[74:75], v[98:99], v[102:103]
	v_cvt_f32_i32_e32 v67, v67
	v_add_f32_e32 v75, v75, v95
	v_add_f32_e32 v95, v74, v75
	v_mul_f32_e32 v74, 0x3d372713, v95
	v_mul_f32_e32 v74, v95, v74
	v_fma_f32 v74, v95, v74, v95
	v_mul_f32_e32 v74, 0x3f4c422a, v74
	v_add_f32_e32 v74, v74, v74
	v_cvt_f32_i32_e32 v66, v66
	v_mul_f32_e32 v74, 0xbfb8aa3b, v74
	v_exp_f32_e32 v74, v74
	v_mul_f32_e32 v75, v85, v94
	v_pk_mul_f32 v[66:67], v[122:123], v[66:67]
	v_mov_b32_e32 v85, v76
	v_pk_mul_f32 v[66:67], v[208:209], v[66:67]
	v_add_f32_e32 v74, 1.0, v74
	v_mul_f32_e32 v66, v66, v75
	v_rcp_f32_e32 v94, v74
	v_fma_f32 v83, v92, v83, v112
	v_pk_mul_f32 v[74:75], v[114:115], v[84:85]
	v_fma_f32 v85, v93, v106, v113
	v_add_f32_e32 v75, v75, v83
	v_add_f32_e32 v76, v74, v75
	v_mul_f32_e32 v74, 0x3d372713, v76
	v_mul_f32_e32 v74, v76, v74
	v_fma_f32 v74, v76, v74, v76
	v_mul_f32_e32 v74, 0x3f4c422a, v74
	v_add_f32_e32 v74, v74, v74
	v_mul_f32_e32 v74, 0xbfb8aa3b, v74
	v_mov_b32_e32 v83, v77
	v_exp_f32_e32 v84, v74
	v_pk_mul_f32 v[74:75], v[100:101], v[82:83]
	v_mul_f32_e32 v77, v95, v94
	v_add_f32_e32 v75, v75, v85
	v_add_f32_e32 v74, v74, v75
	v_mul_f32_e32 v75, 0x3d372713, v74
	v_mul_f32_e32 v75, v74, v75
	v_fma_f32 v75, v74, v75, v74
	v_mul_f32_e32 v75, 0x3f4c422a, v75
	v_add_f32_e32 v75, v75, v75
	v_mul_f32_e32 v75, 0xbfb8aa3b, v75
	v_exp_f32_e32 v75, v75
	v_add_f32_e32 v82, 1.0, v84
	v_rcp_f32_e32 v82, v82
	v_mul_f32_e32 v67, v67, v77
	v_add_f32_e32 v75, 1.0, v75
	v_rcp_f32_e32 v75, v75
	v_mul_f32_e32 v76, v76, v82
	v_mul_f32_e32 v68, v68, v76
	v_cvt_pk_bf16_f32 v66, v66, v67
	v_mul_f32_e32 v74, v74, v75
	v_mul_f32_e32 v69, v69, v74
	v_cvt_pk_bf16_f32 v67, v68, v69
	s_mov_b64 s[2:3], -1
	s_and_b64 vcc, exec, s[62:63]
	global_store_dwordx2 v[138:139], v[66:67], off offset:8
	s_cbranch_vccz .LBB0_2662
	v_cndmask_b32_e64 v67, v78, v86, s[16:17]
	v_cndmask_b32_e64 v68, v79, v87, s[16:17]
	s_nop 0
	v_mov_b32_dpp v66, v67 row_ror:1 row_mask:0xf bank_mask:0xf
	v_cndmask_b32_e64 v67, v86, v78, s[38:39]
	v_cndmask_b32_e64 v69, v80, v88, s[16:17]
	s_nop 0
	v_mov_b32_dpp v94, v67 row_ror:2 row_mask:0xf bank_mask:0xf
	v_cndmask_b32_e64 v74, v81, v89, s[16:17]
	v_mov_b32_dpp v67, v68 row_ror:1 row_mask:0xf bank_mask:0xf
	v_cndmask_b32_e64 v68, v87, v79, s[38:39]
	s_mov_b64 s[2:3], 0
	s_nop 0
	v_mov_b32_dpp v83, v68 row_ror:2 row_mask:0xf bank_mask:0xf
	v_mov_b32_e32 v76, v79
	s_nop 0
	v_mov_b32_dpp v68, v69 row_ror:1 row_mask:0xf bank_mask:0xf
	v_cndmask_b32_e64 v69, v88, v80, s[38:39]
	s_nop 1
	v_mov_b32_dpp v75, v69 row_ror:2 row_mask:0xf bank_mask:0xf
	s_nop 1
	v_mov_b32_dpp v69, v74 row_ror:1 row_mask:0xf bank_mask:0xf
	v_cndmask_b32_e64 v74, v89, v81, s[38:39]
	s_nop 1
	v_mov_b32_dpp v82, v74 row_ror:2 row_mask:0xf bank_mask:0xf
	v_mov_b32_e32 v74, v81

; __device__ __forceinline__ float dpp_ror1(float v) { return __builtin_bit_cast(float, __builtin_amdgcn_update_dpp(0, __builtin_bit_cast(int, v), 0x121, 0xf, 0xf, false)); }
; __device__ __forceinline__ float dpp_ror2(float v) { return __builtin_bit_cast(float, __builtin_amdgcn_update_dpp(0, __builtin_bit_cast(int, v), 0x122, 0xf, 0xf, false)); }
;     __device__ __forceinline__ void operator()(f32x4 (&acc)[2][2][4][2], const pg8::Unit& u, int wr, int wc, int fr, int fq) const {
;     ...
;                     else { const int t = fr & 3; const float* sp = stf + (size_t)((row - MP) >> 2) * 2 * DFF + ch0 + 4 * n;
;                         f32x4 b0 = (f32x4){0.f, 0.f, 0.f, 0.f}, b1 = b0; if (t == 0) b0 = *(const f32x4*)sp; if (t <= 1) b1 = *(const f32x4*)(sp + DFF);
; #pragma unroll
;                         for (int j = 0; j < 4; ++j) { const float r1 = dpp_ror1(g[j]), r2 = dpp_ror2(g[j]); p1[j] = t >= 1 ? r1 : b1[j]; p2[j] = t >= 2 ? r2 : (t == 1 ? b1[j] : b0[j]); } }
.LBB0_2667:
	s_or_b64 exec, exec, s[2:3]
	s_waitcnt vmcnt(0)
	v_cndmask_b32_e64 v68, v74, v82, s[14:15]
	v_cndmask_b32_e64 v69, v75, v83, s[14:15]
	v_mov_b32_dpp v67, v78 row_ror:2 row_mask:0xf bank_mask:0xf
	v_cndmask_b32_e64 v94, v68, v67, s[12:13]
	v_cndmask_b32_e64 v74, v76, v84, s[14:15]
	v_mov_b32_dpp v67, v79 row_ror:1 row_mask:0xf bank_mask:0xf
	v_mov_b32_dpp v68, v79 row_ror:2 row_mask:0xf bank_mask:0xf
	v_cndmask_b32_e64 v67, v67, v83, s[10:11]
	v_cndmask_b32_e64 v83, v69, v68, s[12:13]
	v_mov_b32_dpp v69, v80 row_ror:2 row_mask:0xf bank_mask:0xf
	v_cndmask_b32_e64 v75, v74, v69, s[12:13]
	v_mov_b32_dpp v66, v78 row_ror:1 row_mask:0xf bank_mask:0xf
	v_mov_b32_dpp v68, v80 row_ror:1 row_mask:0xf bank_mask:0xf
	v_mov_b32_dpp v69, v81 row_ror:1 row_mask:0xf bank_mask:0xf
	v_mov_b32_dpp v74, v81 row_ror:2 row_mask:0xf bank_mask:0xf
	v_cndmask_b32_e64 v76, v77, v85, s[14:15]
	v_cndmask_b32_e64 v66, v66, v82, s[10:11]
	v_cndmask_b32_e64 v68, v68, v84, s[10:11]
	v_cndmask_b32_e64 v69, v69, v85, s[10:11]
	v_cndmask_b32_e64 v82, v76, v74, s[12:13]
	s_mov_b64 s[2:3], -1
	v_mov_b32_e32 v76, v79
	v_mov_b32_e32 v74, v81

; __device__ __forceinline__ float dpp_ror1(float v) { return __builtin_bit_cast(float, __builtin_amdgcn_update_dpp(0, __builtin_bit_cast(int, v), 0x121, 0xf, 0xf, false)); }
; __device__ __forceinline__ float dpp_ror2(float v) { return __builtin_bit_cast(float, __builtin_amdgcn_update_dpp(0, __builtin_bit_cast(int, v), 0x122, 0xf, 0xf, false)); }
;     __device__ __forceinline__ void operator()(f32x4 (&acc)[2][2][4][2], const pg8::Unit& u, int wr, int wc, int fr, int fq) const {
;     ...
;             for (int n = 0; n < 2; ++n) {
;                 const f32x4 w0 = *(const f32x4*)(cw + ch0 + 4 * n), w1 = *(const f32x4*)(cw + DFF + ch0 + 4 * n), w2 = *(const f32x4*)(cw + 2 * DFF + ch0 + 4 * n), bb = *(const f32x4*)(cb + ch0 + 4 * n);
; #pragma unroll
;                 for (int m = 0; m < 4; ++m) { const int row = row0 + ai * 128 + m * 16; const f32x4 g = acc[ai][0][m][n], vv = acc[ai][1][m][n]; f32x4 p1, p2;
;                     if (prompt) { const f32x4 gp = (m == 0) ? hal[n] : acc[ai][0][m > 0 ? m - 1 : 0][n];
; #pragma unroll
;                         for (int j = 0; j < 4; ++j) { p1[j] = dpp_ror1(fr == 15 ? gp[j] : g[j]); p2[j] = dpp_ror2(fr >= 14 ? gp[j] : g[j]); } }
.LBB0_2670:
	s_or_b64 exec, exec, s[20:21]
	global_load_dwordx4 v[78:81], v[202:203], off
	global_load_dwordx4 v[66:69], v[214:215], off
	global_load_dwordx4 v[82:85], v[216:217], off
	global_load_dwordx4 v[74:77], v[204:205], off
	s_mov_b64 s[2:3], -1
	s_and_b64 vcc, exec, s[62:63]
	s_cbranch_vccz .LBB0_2672
	s_waitcnt lgkmcnt(1)
	v_cndmask_b32_e64 v87, v70, v90, s[16:17]
	v_cndmask_b32_e64 v88, v71, v91, s[16:17]
	s_nop 0
	v_mov_b32_dpp v86, v87 row_ror:1 row_mask:0xf bank_mask:0xf
	v_cndmask_b32_e64 v87, v90, v70, s[38:39]
	v_cndmask_b32_e64 v89, v72, v92, s[16:17]
	s_nop 0
	v_mov_b32_dpp v101, v87 row_ror:2 row_mask:0xf bank_mask:0xf
	v_cndmask_b32_e64 v90, v73, v93, s[16:17]
	v_mov_b32_dpp v87, v88 row_ror:1 row_mask:0xf bank_mask:0xf
	v_cndmask_b32_e64 v88, v91, v71, s[38:39]
	s_mov_b64 s[2:3], 0
	s_nop 0
	v_mov_b32_dpp v99, v88 row_ror:2 row_mask:0xf bank_mask:0xf
	v_mov_b32_e32 v100, v70
	v_mov_b32_e32 v98, v71
	v_mov_b32_dpp v88, v89 row_ror:1 row_mask:0xf bank_mask:0xf
	v_cndmask_b32_e64 v89, v92, v72, s[38:39]
	v_mov_b32_e32 v96, v72
	v_mov_b32_e32 v94, v73
	v_mov_b32_dpp v97, v89 row_ror:2 row_mask:0xf bank_mask:0xf
	s_nop 1
	v_mov_b32_dpp v89, v90 row_ror:1 row_mask:0xf bank_mask:0xf
	v_cndmask_b32_e64 v90, v93, v73, s[38:39]
	s_nop 1
	v_mov_b32_dpp v95, v90 row_ror:2 row_mask:0xf bank_mask:0xf

; __device__ __forceinline__ unsigned cvt_pk_bf16(float lo, float hi) { unsigned r; asm("v_cvt_pk_bf16_f32 %0, %1, %2" : "=v"(r) : "v"(lo), "v"(hi)); return r; }
;     __device__ __forceinline__ void operator()(f32x4 (&acc)[2][2][4][2], const pg8::Unit& u, int wr, int wc, int fr, int fq) const {
;     ...
;                 for (int n = 0; n < 2; ++n) { const u32x4 c = *(const u32x4*)(cmax + u.pn * 256 + bj * 128 + cl0 + 4 * n); sw[bj][n] = (f32x4){__uint_as_float(c.x), __uint_as_float(c.y), __uint_as_float(c.z), __uint_as_float(c.w)} * (1.004f / 127.0f); }
; #pragma unroll
;             for (int ai = 0; ai < 2; ++ai)
; #pragma unroll
;                 for (int m = 0; m < 4; ++m)
; #pragma unroll
;                     for (int bj = 0; bj < 2; ++bj)
; #pragma unroll
;                         for (int n = 0; n < 2; ++n) { const i32x4 q = __builtin_bit_cast(i32x4, acc[ai][bj][m][n]); acc[ai][bj][m][n] = (f32x4){(float)q[0], (float)q[1], (float)q[2], (float)q[3]} * sw[bj][n] * sc[ai][m]; }
;     ...
;                 for (int m = 0; m < 4; ++m) { const int row = row0 + ai * 128 + m * 16; const f32x4 g = acc[ai][0][m][n], vv = acc[ai][1][m][n]; f32x4 p1, p2;
;                     if (prompt) { const f32x4 gp = (m == 0) ? hal[n] : acc[ai][0][m > 0 ? m - 1 : 0][n];
; #pragma unroll
;                         for (int j = 0; j < 4; ++j) { p1[j] = dpp_ror1(fr == 15 ? gp[j] : g[j]); p2[j] = dpp_ror2(fr >= 14 ? gp[j] : g[j]); } }
;                     else { const int t = fr & 3; const float* sp = stf + (size_t)((row - MP) >> 2) * 2 * DFF + ch0 + 4 * n;
;                         f32x4 b0 = (f32x4){0.f, 0.f, 0.f, 0.f}, b1 = b0; if (t == 0) b0 = *(const f32x4*)sp; if (t <= 1) b1 = *(const f32x4*)(sp + DFF);
; #pragma unroll
;                         for (int j = 0; j < 4; ++j) { const float r1 = dpp_ror1(g[j]), r2 = dpp_ror2(g[j]); p1[j] = t >= 1 ? r1 : b1[j]; p2[j] = t >= 2 ? r2 : (t == 1 ? b1[j] : b0[j]); } }
;                     float o[4];
; #pragma unroll
;                     for (int j = 0; j < 4; ++j) { const float y = bb[j] + w0[j] * p2[j] + w1[j] * p1[j] + w2[j] * g[j]; o[j] = gelu_tanh(y) * vv[j]; }
;                     u32x2 w; w.x = cvt_pk_bf16(o[0], o[1]); w.y = cvt_pk_bf16(o[2], o[3]);
;                     *(u32x2*)(ACT + (size_t)row * DFF + ch0 + 4 * n) = w; } } }
.LBB0_2677:
	s_or_b64 exec, exec, s[2:3]
	s_waitcnt vmcnt(0)
	v_cndmask_b32_e64 v88, v88, v92, s[14:15]
	v_cndmask_b32_e64 v89, v89, v93, s[14:15]
	v_mov_b32_dpp v87, v70 row_ror:2 row_mask:0xf bank_mask:0xf
	v_cndmask_b32_e64 v101, v88, v87, s[12:13]
	v_cndmask_b32_e64 v90, v90, v94, s[14:15]
	v_mov_b32_dpp v88, v71 row_ror:2 row_mask:0xf bank_mask:0xf
	v_cndmask_b32_e64 v99, v89, v88, s[12:13]
	v_mov_b32_dpp v89, v72 row_ror:2 row_mask:0xf bank_mask:0xf
	v_cndmask_b32_e64 v97, v90, v89, s[12:13]
	v_mov_b32_dpp v86, v70 row_ror:1 row_mask:0xf bank_mask:0xf
	v_mov_b32_dpp v87, v71 row_ror:1 row_mask:0xf bank_mask:0xf
	v_mov_b32_dpp v88, v72 row_ror:1 row_mask:0xf bank_mask:0xf
	v_mov_b32_dpp v89, v73 row_ror:1 row_mask:0xf bank_mask:0xf
	v_mov_b32_dpp v90, v73 row_ror:2 row_mask:0xf bank_mask:0xf
	v_cndmask_b32_e64 v91, v91, v95, s[14:15]
	v_cndmask_b32_e64 v86, v86, v92, s[10:11]
	v_cndmask_b32_e64 v87, v87, v93, s[10:11]
	v_cndmask_b32_e64 v88, v88, v94, s[10:11]
	v_cndmask_b32_e64 v89, v89, v95, s[10:11]
	v_cndmask_b32_e64 v95, v91, v90, s[12:13]
	v_mov_b32_e32 v100, v70
	v_mov_b32_e32 v98, v71
	v_mov_b32_e32 v96, v72
	v_mov_b32_e32 v94, v73
.LBB0_2678:
	s_waitcnt vmcnt(0)
	v_fma_f32 v103, v78, v101, v74
	s_waitcnt lgkmcnt(1)
	v_mov_b32_e32 v90, v82
	v_mov_b32_e32 v91, v66
	v_mov_b32_e32 v101, v86
	v_pk_mul_f32 v[92:93], v[90:91], v[100:101]
	v_cvt_f32_i32_e32 v49, v49
	v_add_f32_e32 v66, v93, v103
	v_add_f32_e32 v86, v92, v66
	v_mul_f32_e32 v66, 0x3d372713, v86
	v_mul_f32_e32 v66, v86, v66
	v_fma_f32 v66, v86, v66, v86
	v_mul_f32_e32 v66, 0x3f4c422a, v66
	v_add_f32_e32 v66, v66, v66
	v_mul_f32_e32 v66, 0xbfb8aa3b, v66
	v_cvt_f32_i32_e32 v48, v48
	v_exp_f32_e32 v66, v66
	v_mov_b32_e32 v92, v198
	v_mov_b32_e32 v93, v198
	v_pk_mul_f32 v[48:49], v[160:161], v[48:49]
	v_add_f32_e32 v66, 1.0, v66
	v_pk_mul_f32 v[48:49], v[92:93], v[48:49]
	v_rcp_f32_e32 v92, v66
	v_fma_f32 v93, v79, v99, v75
	v_mov_b32_e32 v66, v83
	v_mov_b32_e32 v99, v87
	v_pk_mul_f32 v[82:83], v[66:67], v[98:99]
	v_cvt_f32_i32_e32 v47, v47
	v_add_f32_e32 v83, v83, v93
	v_add_f32_e32 v87, v82, v83
	v_mul_f32_e32 v82, 0x3d372713, v87
	v_mul_f32_e32 v82, v87, v82
	v_fma_f32 v82, v87, v82, v87
	v_mul_f32_e32 v82, 0x3f4c422a, v82
	v_add_f32_e32 v82, v82, v82
	v_cvt_f32_i32_e32 v46, v46
	v_mul_f32_e32 v82, 0xbfb8aa3b, v82
	v_exp_f32_e32 v82, v82
	v_mul_f32_e32 v83, v86, v92
	v_pk_mul_f32 v[46:47], v[158:159], v[46:47]
	v_fma_f32 v98, v80, v97, v76
	v_pk_mul_f32 v[46:47], v[198:199], v[46:47]
	v_add_f32_e32 v82, 1.0, v82
	v_mov_b32_e32 v92, v84
	v_mov_b32_e32 v93, v68
	v_mov_b32_e32 v97, v88
	v_mul_f32_e32 v46, v46, v83
	v_rcp_f32_e32 v86, v82
	v_pk_mul_f32 v[82:83], v[92:93], v[96:97]
	v_fma_f32 v96, v81, v95, v77
	v_add_f32_e32 v68, v83, v98
	v_add_f32_e32 v84, v82, v68
	v_mul_f32_e32 v68, 0x3d372713, v84
	v_mul_f32_e32 v68, v84, v68
	v_fma_f32 v68, v84, v68, v84
	v_mul_f32_e32 v68, 0x3f4c422a, v68
	v_add_f32_e32 v68, v68, v68
	v_mul_f32_e32 v68, 0xbfb8aa3b, v68
	v_exp_f32_e32 v88, v68
	v_mov_b32_e32 v68, v85
	v_mov_b32_e32 v95, v89
	v_pk_mul_f32 v[82:83], v[68:69], v[94:95]
	v_mul_f32_e32 v85, v87, v86
	v_add_f32_e32 v83, v83, v96
	v_add_f32_e32 v82, v82, v83
	v_mul_f32_e32 v83, 0x3d372713, v82
	v_mul_f32_e32 v83, v82, v83
	v_fma_f32 v83, v82, v83, v82
	v_mul_f32_e32 v83, 0x3f4c422a, v83
	v_add_f32_e32 v83, v83, v83
	v_mul_f32_e32 v83, 0xbfb8aa3b, v83
	v_exp_f32_e32 v83, v83
	v_add_f32_e32 v86, 1.0, v88
	v_rcp_f32_e32 v86, v86
	v_mul_f32_e32 v47, v47, v85
	v_add_f32_e32 v83, 1.0, v83
	v_rcp_f32_e32 v83, v83
	v_mul_f32_e32 v84, v84, v86
	v_mul_f32_e32 v48, v48, v84
	v_cvt_pk_bf16_f32 v46, v46, v47
	v_mul_f32_e32 v82, v82, v83
	v_mul_f32_e32 v49, v49, v82
	v_cvt_pk_bf16_f32 v47, v48, v49
	v_mov_b64_e32 v[48:49], s[24:25]
	v_mad_i64_i32 v[48:49], s[2:3], v219, s83, v[48:49]
	v_lshl_add_u64 v[86:87], v[194:195], 1, v[48:49]
	s_mov_b64 s[2:3], -1
	s_and_b64 vcc, exec, s[62:63]
	global_store_dwordx2 v[86:87], v[46:47], off
	s_cbranch_vccz .LBB0_2680
	v_cndmask_b32_e64 v47, v62, v70, s[16:17]
	v_cndmask_b32_e64 v48, v63, v71, s[16:17]
	s_nop 0
	v_mov_b32_dpp v46, v47 row_ror:1 row_mask:0xf bank_mask:0xf
	v_cndmask_b32_e64 v47, v70, v62, s[38:39]
	v_cndmask_b32_e64 v49, v64, v72, s[16:17]
	s_nop 0
	v_mov_b32_dpp v95, v47 row_ror:2 row_mask:0xf bank_mask:0xf
	v_cndmask_b32_e64 v70, v65, v73, s[16:17]
	v_mov_b32_dpp v47, v48 row_ror:1 row_mask:0xf bank_mask:0xf
	v_cndmask_b32_e64 v48, v71, v63, s[38:39]
	s_mov_b64 s[2:3], 0
	s_nop 0
	v_mov_b32_dpp v89, v48 row_ror:2 row_mask:0xf bank_mask:0xf
	v_mov_b32_e32 v94, v62
	v_mov_b32_e32 v88, v63
	v_mov_b32_dpp v48, v49 row_ror:1 row_mask:0xf bank_mask:0xf
	v_cndmask_b32_e64 v49, v72, v64, s[38:39]
	v_mov_b32_e32 v84, v64
	v_mov_b32_e32 v82, v65
	v_mov_b32_dpp v83, v49 row_ror:2 row_mask:0xf bank_mask:0xf
	s_nop 1
	v_mov_b32_dpp v49, v70 row_ror:1 row_mask:0xf bank_mask:0xf
	v_cndmask_b32_e64 v70, v73, v65, s[38:39]
	s_nop 1
	v_mov_b32_dpp v97, v70 row_ror:2 row_mask:0xf bank_mask:0xf

; __device__ __forceinline__ unsigned cvt_pk_bf16(float lo, float hi) { unsigned r; asm("v_cvt_pk_bf16_f32 %0, %1, %2" : "=v"(r) : "v"(lo), "v"(hi)); return r; }
;     __device__ __forceinline__ void operator()(f32x4 (&acc)[2][2][4][2], const pg8::Unit& u, int wr, int wc, int fr, int fq) const {
;     ...
;                 for (int n = 0; n < 2; ++n) { const u32x4 c = *(const u32x4*)(cmax + u.pn * 256 + bj * 128 + cl0 + 4 * n); sw[bj][n] = (f32x4){__uint_as_float(c.x), __uint_as_float(c.y), __uint_as_float(c.z), __uint_as_float(c.w)} * (1.004f / 127.0f); }
; #pragma unroll
;             for (int ai = 0; ai < 2; ++ai)
; #pragma unroll
;                 for (int m = 0; m < 4; ++m)
; #pragma unroll
;                     for (int bj = 0; bj < 2; ++bj)
; #pragma unroll
;                         for (int n = 0; n < 2; ++n) { const i32x4 q = __builtin_bit_cast(i32x4, acc[ai][bj][m][n]); acc[ai][bj][m][n] = (f32x4){(float)q[0], (float)q[1], (float)q[2], (float)q[3]} * sw[bj][n] * sc[ai][m]; }
;     ...
;                 for (int m = 0; m < 4; ++m) { const int row = row0 + ai * 128 + m * 16; const f32x4 g = acc[ai][0][m][n], vv = acc[ai][1][m][n]; f32x4 p1, p2;
;                     if (prompt) { const f32x4 gp = (m == 0) ? hal[n] : acc[ai][0][m > 0 ? m - 1 : 0][n];
; #pragma unroll
;                         for (int j = 0; j < 4; ++j) { p1[j] = dpp_ror1(fr == 15 ? gp[j] : g[j]); p2[j] = dpp_ror2(fr >= 14 ? gp[j] : g[j]); } }
;                     else { const int t = fr & 3; const float* sp = stf + (size_t)((row - MP) >> 2) * 2 * DFF + ch0 + 4 * n;
;                         f32x4 b0 = (f32x4){0.f, 0.f, 0.f, 0.f}, b1 = b0; if (t == 0) b0 = *(const f32x4*)sp; if (t <= 1) b1 = *(const f32x4*)(sp + DFF);
; #pragma unroll
;                         for (int j = 0; j < 4; ++j) { const float r1 = dpp_ror1(g[j]), r2 = dpp_ror2(g[j]); p1[j] = t >= 1 ? r1 : b1[j]; p2[j] = t >= 2 ? r2 : (t == 1 ? b1[j] : b0[j]); } }
;                     float o[4];
; #pragma unroll
;                     for (int j = 0; j < 4; ++j) { const float y = bb[j] + w0[j] * p2[j] + w1[j] * p1[j] + w2[j] * g[j]; o[j] = gelu_tanh(y) * vv[j]; }
;                     u32x2 w; w.x = cvt_pk_bf16(o[0], o[1]); w.y = cvt_pk_bf16(o[2], o[3]);
;                     *(u32x2*)(ACT + (size_t)row * DFF + ch0 + 4 * n) = w; } } }
.LBB0_2685:
	s_or_b64 exec, exec, s[2:3]
	s_waitcnt vmcnt(0)
	v_cndmask_b32_e64 v48, v70, v82, s[14:15]
	v_cndmask_b32_e64 v49, v71, v83, s[14:15]
	v_mov_b32_dpp v47, v62 row_ror:2 row_mask:0xf bank_mask:0xf
	v_cndmask_b32_e64 v95, v48, v47, s[12:13]
	v_cndmask_b32_e64 v70, v72, v84, s[14:15]
	v_mov_b32_dpp v48, v63 row_ror:2 row_mask:0xf bank_mask:0xf
	v_cndmask_b32_e64 v89, v49, v48, s[12:13]
	v_mov_b32_dpp v47, v63 row_ror:1 row_mask:0xf bank_mask:0xf
	v_mov_b32_dpp v49, v64 row_ror:2 row_mask:0xf bank_mask:0xf
	v_cndmask_b32_e64 v47, v47, v83, s[10:11]
	v_cndmask_b32_e64 v83, v70, v49, s[12:13]
	v_mov_b32_dpp v46, v62 row_ror:1 row_mask:0xf bank_mask:0xf
	v_mov_b32_dpp v48, v64 row_ror:1 row_mask:0xf bank_mask:0xf
	v_mov_b32_dpp v49, v65 row_ror:1 row_mask:0xf bank_mask:0xf
	v_mov_b32_dpp v70, v65 row_ror:2 row_mask:0xf bank_mask:0xf
	v_cndmask_b32_e64 v71, v73, v85, s[14:15]
	v_cndmask_b32_e64 v46, v46, v82, s[10:11]
	v_cndmask_b32_e64 v48, v48, v84, s[10:11]
	v_cndmask_b32_e64 v49, v49, v85, s[10:11]
	v_cndmask_b32_e64 v97, v71, v70, s[12:13]
	v_mov_b32_e32 v94, v62
	v_mov_b32_e32 v88, v63
	v_mov_b32_e32 v84, v64
	v_mov_b32_e32 v82, v65
.LBB0_2686:
	v_fma_f32 v73, v78, v95, v74
	v_mov_b32_e32 v95, v46
	v_pk_mul_f32 v[70:71], v[90:91], v[94:95]
	v_cvt_f32_i32_e32 v45, v45
	v_add_f32_e32 v46, v71, v73
	v_add_f32_e32 v73, v70, v46
	v_mul_f32_e32 v46, 0x3d372713, v73
	v_mul_f32_e32 v46, v73, v46
	v_fma_f32 v46, v73, v46, v73
	v_mul_f32_e32 v46, 0x3f4c422a, v46
	v_add_f32_e32 v46, v46, v46
	v_cvt_f32_i32_e32 v44, v44
	v_mul_f32_e32 v46, 0xbfb8aa3b, v46
	v_exp_f32_e32 v46, v46
	v_mov_b32_e32 v70, v196
	v_pk_mul_f32 v[44:45], v[160:161], v[44:45]
	v_mov_b32_e32 v71, v196
	v_pk_mul_f32 v[44:45], v[70:71], v[44:45]
	v_add_f32_e32 v46, 1.0, v46
	v_fma_f32 v71, v79, v89, v75
	v_mov_b32_e32 v89, v47
	v_rcp_f32_e32 v70, v46
	v_pk_mul_f32 v[46:47], v[66:67], v[88:89]
	v_cvt_f32_i32_e32 v43, v43
	v_add_f32_e32 v47, v47, v71
	v_add_f32_e32 v71, v46, v47
	v_mul_f32_e32 v46, 0x3d372713, v71
	v_mul_f32_e32 v46, v71, v46
	v_fma_f32 v46, v71, v46, v71
	v_mul_f32_e32 v46, 0x3f4c422a, v46
	v_add_f32_e32 v46, v46, v46
	v_cvt_f32_i32_e32 v42, v42
	v_mul_f32_e32 v46, 0xbfb8aa3b, v46
	v_exp_f32_e32 v46, v46
	v_mul_f32_e32 v47, v73, v70
	v_pk_mul_f32 v[42:43], v[158:159], v[42:43]
	v_mov_b32_e32 v85, v48
	v_pk_mul_f32 v[42:43], v[196:197], v[42:43]
	v_add_f32_e32 v46, 1.0, v46
	v_mul_f32_e32 v42, v42, v47
	v_rcp_f32_e32 v70, v46
	v_fma_f32 v73, v80, v83, v76
	v_pk_mul_f32 v[46:47], v[92:93], v[84:85]
	v_mov_b32_e32 v83, v49
	v_add_f32_e32 v47, v47, v73
	v_add_f32_e32 v48, v46, v47
	v_mul_f32_e32 v46, 0x3d372713, v48
	v_mul_f32_e32 v46, v48, v46
	v_fma_f32 v46, v48, v46, v48
	v_mul_f32_e32 v46, 0x3f4c422a, v46
	v_add_f32_e32 v46, v46, v46
	v_mul_f32_e32 v46, 0xbfb8aa3b, v46
	v_exp_f32_e32 v73, v46
	v_fma_f32 v84, v81, v97, v77
	v_pk_mul_f32 v[46:47], v[68:69], v[82:83]
	v_mul_f32_e32 v49, v71, v70
	v_add_f32_e32 v47, v47, v84
	v_add_f32_e32 v46, v46, v47
	v_mul_f32_e32 v47, 0x3d372713, v46
	v_mul_f32_e32 v47, v46, v47
	v_fma_f32 v47, v46, v47, v46
	v_mul_f32_e32 v47, 0x3f4c422a, v47
	v_add_f32_e32 v47, v47, v47
	v_mul_f32_e32 v47, 0xbfb8aa3b, v47
	v_exp_f32_e32 v47, v47
	v_add_f32_e32 v70, 1.0, v73
	v_rcp_f32_e32 v70, v70
	v_mul_f32_e32 v43, v43, v49
	v_add_f32_e32 v47, 1.0, v47
	v_rcp_f32_e32 v47, v47
	v_mul_f32_e32 v48, v48, v70
	v_mul_f32_e32 v44, v44, v48
	v_add_u32_e32 v72, 0x90, v200
	v_mul_f32_e32 v46, v46, v47
	v_mul_f32_e32 v45, v45, v46
	v_cvt_pk_bf16_f32 v42, v42, v43
	v_cvt_pk_bf16_f32 v43, v44, v45
	v_mov_b64_e32 v[44:45], s[24:25]
	v_mad_i64_i32 v[44:45], s[2:3], v72, s83, v[44:45]
	v_lshl_add_u64 v[70:71], v[194:195], 1, v[44:45]
	s_mov_b64 s[2:3], -1
	s_and_b64 vcc, exec, s[62:63]
	global_store_dwordx2 v[70:71], v[42:43], off
	s_cbranch_vccz .LBB0_2688
	v_cndmask_b32_e64 v43, v54, v62, s[16:17]
	v_cndmask_b32_e64 v44, v55, v63, s[16:17]
	s_nop 0
	v_mov_b32_dpp v42, v43 row_ror:1 row_mask:0xf bank_mask:0xf
	v_cndmask_b32_e64 v43, v62, v54, s[38:39]
	v_cndmask_b32_e64 v45, v56, v64, s[16:17]
	s_nop 0
	v_mov_b32_dpp v83, v43 row_ror:2 row_mask:0xf bank_mask:0xf
	v_cndmask_b32_e64 v46, v57, v65, s[16:17]
	v_mov_b32_dpp v43, v44 row_ror:1 row_mask:0xf bank_mask:0xf
	v_cndmask_b32_e64 v44, v63, v55, s[38:39]
	s_mov_b64 s[2:3], 0
	s_nop 0
	v_mov_b32_dpp v73, v44 row_ror:2 row_mask:0xf bank_mask:0xf
	v_mov_b32_e32 v82, v54
	v_mov_b32_e32 v72, v55
	v_mov_b32_dpp v44, v45 row_ror:1 row_mask:0xf bank_mask:0xf
	v_cndmask_b32_e64 v45, v64, v56, s[38:39]
	v_mov_b32_e32 v48, v56
	s_nop 0
	v_mov_b32_dpp v49, v45 row_ror:2 row_mask:0xf bank_mask:0xf
	s_nop 1
	v_mov_b32_dpp v45, v46 row_ror:1 row_mask:0xf bank_mask:0xf
	v_cndmask_b32_e64 v46, v65, v57, s[38:39]
	s_nop 1
	v_mov_b32_dpp v47, v46 row_ror:2 row_mask:0xf bank_mask:0xf
	v_mov_b32_e32 v46, v57

; __device__ __forceinline__ unsigned cvt_pk_bf16(float lo, float hi) { unsigned r; asm("v_cvt_pk_bf16_f32 %0, %1, %2" : "=v"(r) : "v"(lo), "v"(hi)); return r; }
;     __device__ __forceinline__ void operator()(f32x4 (&acc)[2][2][4][2], const pg8::Unit& u, int wr, int wc, int fr, int fq) const {
;     ...
;                 for (int n = 0; n < 2; ++n) { const u32x4 c = *(const u32x4*)(cmax + u.pn * 256 + bj * 128 + cl0 + 4 * n); sw[bj][n] = (f32x4){__uint_as_float(c.x), __uint_as_float(c.y), __uint_as_float(c.z), __uint_as_float(c.w)} * (1.004f / 127.0f); }
; #pragma unroll
;             for (int ai = 0; ai < 2; ++ai)
; #pragma unroll
;                 for (int m = 0; m < 4; ++m)
; #pragma unroll
;                     for (int bj = 0; bj < 2; ++bj)
; #pragma unroll
;                         for (int n = 0; n < 2; ++n) { const i32x4 q = __builtin_bit_cast(i32x4, acc[ai][bj][m][n]); acc[ai][bj][m][n] = (f32x4){(float)q[0], (float)q[1], (float)q[2], (float)q[3]} * sw[bj][n] * sc[ai][m]; }
;     ...
;                 for (int m = 0; m < 4; ++m) { const int row = row0 + ai * 128 + m * 16; const f32x4 g = acc[ai][0][m][n], vv = acc[ai][1][m][n]; f32x4 p1, p2;
;                     if (prompt) { const f32x4 gp = (m == 0) ? hal[n] : acc[ai][0][m > 0 ? m - 1 : 0][n];
; #pragma unroll
;                         for (int j = 0; j < 4; ++j) { p1[j] = dpp_ror1(fr == 15 ? gp[j] : g[j]); p2[j] = dpp_ror2(fr >= 14 ? gp[j] : g[j]); } }
;                     else { const int t = fr & 3; const float* sp = stf + (size_t)((row - MP) >> 2) * 2 * DFF + ch0 + 4 * n;
;                         f32x4 b0 = (f32x4){0.f, 0.f, 0.f, 0.f}, b1 = b0; if (t == 0) b0 = *(const f32x4*)sp; if (t <= 1) b1 = *(const f32x4*)(sp + DFF);
; #pragma unroll
;                         for (int j = 0; j < 4; ++j) { const float r1 = dpp_ror1(g[j]), r2 = dpp_ror2(g[j]); p1[j] = t >= 1 ? r1 : b1[j]; p2[j] = t >= 2 ? r2 : (t == 1 ? b1[j] : b0[j]); } }
;                     float o[4];
; #pragma unroll
;                     for (int j = 0; j < 4; ++j) { const float y = bb[j] + w0[j] * p2[j] + w1[j] * p1[j] + w2[j] * g[j]; o[j] = gelu_tanh(y) * vv[j]; }
;                     u32x2 w; w.x = cvt_pk_bf16(o[0], o[1]); w.y = cvt_pk_bf16(o[2], o[3]);
;                     *(u32x2*)(ACT + (size_t)row * DFF + ch0 + 4 * n) = w; } } }
.LBB0_2693:
	s_or_b64 exec, exec, s[2:3]
	s_waitcnt vmcnt(0)
	v_cndmask_b32_e64 v44, v44, v62, s[14:15]
	v_cndmask_b32_e64 v45, v45, v63, s[14:15]
	v_mov_b32_dpp v43, v54 row_ror:2 row_mask:0xf bank_mask:0xf
	v_cndmask_b32_e64 v83, v44, v43, s[12:13]
	v_cndmask_b32_e64 v46, v46, v64, s[14:15]
	v_mov_b32_dpp v44, v55 row_ror:2 row_mask:0xf bank_mask:0xf
	v_cndmask_b32_e64 v73, v45, v44, s[12:13]
	v_mov_b32_dpp v45, v56 row_ror:2 row_mask:0xf bank_mask:0xf
	v_cndmask_b32_e64 v49, v46, v45, s[12:13]
	v_mov_b32_dpp v42, v54 row_ror:1 row_mask:0xf bank_mask:0xf
	v_mov_b32_dpp v43, v55 row_ror:1 row_mask:0xf bank_mask:0xf
	v_mov_b32_dpp v44, v56 row_ror:1 row_mask:0xf bank_mask:0xf
	v_mov_b32_dpp v45, v57 row_ror:1 row_mask:0xf bank_mask:0xf
	v_mov_b32_dpp v46, v57 row_ror:2 row_mask:0xf bank_mask:0xf
	v_cndmask_b32_e64 v47, v47, v65, s[14:15]
	v_cndmask_b32_e64 v42, v42, v62, s[10:11]
	v_cndmask_b32_e64 v43, v43, v63, s[10:11]
	v_cndmask_b32_e64 v44, v44, v64, s[10:11]
	v_cndmask_b32_e64 v45, v45, v65, s[10:11]
	v_cndmask_b32_e64 v47, v47, v46, s[12:13]
	v_mov_b32_e32 v82, v54
	v_mov_b32_e32 v72, v55
	v_mov_b32_e32 v48, v56
	v_mov_b32_e32 v46, v57
.LBB0_2694:
	v_fma_f32 v65, v78, v83, v74
	v_mov_b32_e32 v83, v42
	v_pk_mul_f32 v[62:63], v[90:91], v[82:83]
	v_cvt_f32_i32_e32 v37, v37
	v_add_f32_e32 v42, v63, v65
	v_add_f32_e32 v65, v62, v42
	v_mul_f32_e32 v42, 0x3d372713, v65
	v_mul_f32_e32 v42, v65, v42
	v_fma_f32 v42, v65, v42, v65
	v_mul_f32_e32 v42, 0x3f4c422a, v42
	v_add_f32_e32 v42, v42, v42
	v_cvt_f32_i32_e32 v36, v36
	v_mul_f32_e32 v42, 0xbfb8aa3b, v42
	v_exp_f32_e32 v42, v42
	v_mov_b32_e32 v62, v192
	v_pk_mul_f32 v[36:37], v[160:161], v[36:37]
	v_mov_b32_e32 v63, v192
	v_pk_mul_f32 v[36:37], v[62:63], v[36:37]
	v_add_f32_e32 v42, 1.0, v42
	v_fma_f32 v63, v79, v73, v75
	v_mov_b32_e32 v73, v43
	v_rcp_f32_e32 v62, v42
	v_pk_mul_f32 v[42:43], v[66:67], v[72:73]
	v_cvt_f32_i32_e32 v35, v35
	v_add_f32_e32 v43, v43, v63
	v_add_f32_e32 v63, v42, v43
	v_mul_f32_e32 v42, 0x3d372713, v63
	v_mul_f32_e32 v42, v63, v42
	v_fma_f32 v42, v63, v42, v63
	v_mul_f32_e32 v42, 0x3f4c422a, v42
	v_add_f32_e32 v42, v42, v42
	v_cvt_f32_i32_e32 v34, v34
	v_mul_f32_e32 v42, 0xbfb8aa3b, v42
	v_exp_f32_e32 v42, v42
	v_mul_f32_e32 v43, v65, v62
	v_pk_mul_f32 v[34:35], v[158:159], v[34:35]
	v_fma_f32 v65, v80, v49, v76
	v_pk_mul_f32 v[34:35], v[192:193], v[34:35]
	v_add_f32_e32 v42, 1.0, v42
	v_mov_b32_e32 v49, v44
	v_mul_f32_e32 v34, v34, v43
	v_rcp_f32_e32 v62, v42
	v_pk_mul_f32 v[42:43], v[92:93], v[48:49]
	v_fma_f32 v49, v81, v47, v77
	v_add_f32_e32 v43, v43, v65
	v_add_f32_e32 v44, v42, v43
	v_mul_f32_e32 v42, 0x3d372713, v44
	v_mul_f32_e32 v42, v44, v42
	v_fma_f32 v42, v44, v42, v44
	v_mul_f32_e32 v42, 0x3f4c422a, v42
	v_add_f32_e32 v42, v42, v42
	v_mul_f32_e32 v42, 0xbfb8aa3b, v42
	v_mov_b32_e32 v47, v45
	v_exp_f32_e32 v48, v42
	v_pk_mul_f32 v[42:43], v[68:69], v[46:47]
	v_mul_f32_e32 v45, v63, v62
	v_add_f32_e32 v43, v43, v49
	v_add_f32_e32 v42, v42, v43
	v_mul_f32_e32 v43, 0x3d372713, v42
	v_mul_f32_e32 v43, v42, v43
	v_fma_f32 v43, v42, v43, v42
	v_mul_f32_e32 v43, 0x3f4c422a, v43
	v_add_f32_e32 v43, v43, v43
	v_mul_f32_e32 v43, 0xbfb8aa3b, v43
	v_exp_f32_e32 v43, v43
	v_add_f32_e32 v46, 1.0, v48
	v_rcp_f32_e32 v46, v46
	v_mul_f32_e32 v35, v35, v45
	v_add_f32_e32 v43, 1.0, v43
	v_rcp_f32_e32 v43, v43
	v_mul_f32_e32 v44, v44, v46
	v_mul_f32_e32 v36, v36, v44
	v_add_u32_e32 v64, 0xa0, v200
	v_mul_f32_e32 v42, v42, v43
	v_mul_f32_e32 v37, v37, v42
	v_cvt_pk_bf16_f32 v34, v34, v35
	v_cvt_pk_bf16_f32 v35, v36, v37
	v_mov_b64_e32 v[36:37], s[24:25]
	v_mad_i64_i32 v[36:37], s[2:3], v64, s83, v[36:37]
	v_lshl_add_u64 v[62:63], v[194:195], 1, v[36:37]
	s_mov_b64 s[2:3], -1
	s_and_b64 vcc, exec, s[62:63]
	global_store_dwordx2 v[62:63], v[34:35], off
	s_cbranch_vccz .LBB0_2696
	v_cndmask_b32_e64 v35, v50, v54, s[16:17]
	v_cndmask_b32_e64 v36, v51, v55, s[16:17]
	s_nop 0
	v_mov_b32_dpp v34, v35 row_ror:1 row_mask:0xf bank_mask:0xf
	v_cndmask_b32_e64 v35, v54, v50, s[38:39]
	v_cndmask_b32_e64 v37, v52, v56, s[16:17]
	s_nop 0
	v_mov_b32_dpp v64, v35 row_ror:2 row_mask:0xf bank_mask:0xf
	v_cndmask_b32_e64 v42, v53, v57, s[16:17]
	v_mov_b32_dpp v35, v36 row_ror:1 row_mask:0xf bank_mask:0xf
	v_cndmask_b32_e64 v36, v55, v51, s[38:39]
	s_mov_b64 s[2:3], 0
	s_nop 0
	v_mov_b32_dpp v47, v36 row_ror:2 row_mask:0xf bank_mask:0xf
	v_mov_b32_e32 v44, v51
	s_nop 0
	v_mov_b32_dpp v36, v37 row_ror:1 row_mask:0xf bank_mask:0xf
	v_cndmask_b32_e64 v37, v56, v52, s[38:39]
	s_nop 1
	v_mov_b32_dpp v43, v37 row_ror:2 row_mask:0xf bank_mask:0xf
	s_nop 1
	v_mov_b32_dpp v37, v42 row_ror:1 row_mask:0xf bank_mask:0xf
	v_cndmask_b32_e64 v42, v57, v53, s[38:39]
	s_nop 1
	v_mov_b32_dpp v46, v42 row_ror:2 row_mask:0xf bank_mask:0xf
	v_mov_b32_e32 v42, v53

; __device__ __forceinline__ unsigned cvt_pk_bf16(float lo, float hi) { unsigned r; asm("v_cvt_pk_bf16_f32 %0, %1, %2" : "=v"(r) : "v"(lo), "v"(hi)); return r; }
; __device__ __forceinline__ float gelu_tanh(float x) { const float u = 0.7978845608028654f * (x + 0.044715f * x * x * x); return x * sigmoidf_(2.0f * u); }
; __device__ __forceinline__ float dpp_ror1(float v) { return __builtin_bit_cast(float, __builtin_amdgcn_update_dpp(0, __builtin_bit_cast(int, v), 0x121, 0xf, 0xf, false)); }
; __device__ __forceinline__ float dpp_ror2(float v) { return __builtin_bit_cast(float, __builtin_amdgcn_update_dpp(0, __builtin_bit_cast(int, v), 0x122, 0xf, 0xf, false)); }
;     __device__ __forceinline__ void operator()(f32x4 (&acc)[2][2][4][2], const pg8::Unit& u, int wr, int wc, int fr, int fq) const {
;     ...
;             for (int n = 0; n < 2; ++n) {
;                 const f32x4 w0 = *(const f32x4*)(cw + ch0 + 4 * n), w1 = *(const f32x4*)(cw + DFF + ch0 + 4 * n), w2 = *(const f32x4*)(cw + 2 * DFF + ch0 + 4 * n), bb = *(const f32x4*)(cb + ch0 + 4 * n);
; #pragma unroll
;                 for (int m = 0; m < 4; ++m) { const int row = row0 + ai * 128 + m * 16; const f32x4 g = acc[ai][0][m][n], vv = acc[ai][1][m][n]; f32x4 p1, p2;
;                     if (prompt) { const f32x4 gp = (m == 0) ? hal[n] : acc[ai][0][m > 0 ? m - 1 : 0][n];
; #pragma unroll
;                         for (int j = 0; j < 4; ++j) { p1[j] = dpp_ror1(fr == 15 ? gp[j] : g[j]); p2[j] = dpp_ror2(fr >= 14 ? gp[j] : g[j]); } }
;                     else { const int t = fr & 3; const float* sp = stf + (size_t)((row - MP) >> 2) * 2 * DFF + ch0 + 4 * n;
;                         f32x4 b0 = (f32x4){0.f, 0.f, 0.f, 0.f}, b1 = b0; if (t == 0) b0 = *(const f32x4*)sp; if (t <= 1) b1 = *(const f32x4*)(sp + DFF);
; #pragma unroll
;                         for (int j = 0; j < 4; ++j) { const float r1 = dpp_ror1(g[j]), r2 = dpp_ror2(g[j]); p1[j] = t >= 1 ? r1 : b1[j]; p2[j] = t >= 2 ? r2 : (t == 1 ? b1[j] : b0[j]); } }
;                     float o[4];
; #pragma unroll
;                     for (int j = 0; j < 4; ++j) { const float y = bb[j] + w0[j] * p2[j] + w1[j] * p1[j] + w2[j] * g[j]; o[j] = gelu_tanh(y) * vv[j]; }
;                     u32x2 w; w.x = cvt_pk_bf16(o[0], o[1]); w.y = cvt_pk_bf16(o[2], o[3]);
;                     *(u32x2*)(ACT + (size_t)row * DFF + ch0 + 4 * n) = w; } } }
.LBB0_2701:
	s_or_b64 exec, exec, s[2:3]
	s_waitcnt vmcnt(0)
	v_cndmask_b32_e64 v36, v42, v46, s[14:15]
	v_cndmask_b32_e64 v37, v43, v47, s[14:15]
	v_mov_b32_dpp v35, v50 row_ror:2 row_mask:0xf bank_mask:0xf
	v_cndmask_b32_e64 v64, v36, v35, s[12:13]
	v_cndmask_b32_e64 v42, v44, v48, s[14:15]
	v_mov_b32_dpp v35, v51 row_ror:1 row_mask:0xf bank_mask:0xf
	v_mov_b32_dpp v36, v51 row_ror:2 row_mask:0xf bank_mask:0xf
	v_cndmask_b32_e64 v35, v35, v47, s[10:11]
	v_cndmask_b32_e64 v47, v37, v36, s[12:13]
	v_mov_b32_dpp v37, v52 row_ror:2 row_mask:0xf bank_mask:0xf
	v_cndmask_b32_e64 v43, v42, v37, s[12:13]
	v_mov_b32_dpp v34, v50 row_ror:1 row_mask:0xf bank_mask:0xf
	v_mov_b32_dpp v36, v52 row_ror:1 row_mask:0xf bank_mask:0xf
	v_mov_b32_dpp v37, v53 row_ror:1 row_mask:0xf bank_mask:0xf
	v_mov_b32_dpp v42, v53 row_ror:2 row_mask:0xf bank_mask:0xf
	v_cndmask_b32_e64 v44, v45, v49, s[14:15]
	v_cndmask_b32_e64 v34, v34, v46, s[10:11]
	v_cndmask_b32_e64 v36, v36, v48, s[10:11]
	v_cndmask_b32_e64 v37, v37, v49, s[10:11]
	v_cndmask_b32_e64 v46, v44, v42, s[12:13]
	v_mov_b32_e32 v44, v51
	v_mov_b32_e32 v42, v53
.LBB0_2702:
	v_mov_b32_e32 v51, v34
	v_fma_f32 v45, v78, v64, v74
	v_pk_mul_f32 v[48:49], v[90:91], v[50:51]
	v_cvt_f32_i32_e32 v25, v25
	v_add_f32_e32 v34, v49, v45
	v_add_f32_e32 v50, v48, v34
	v_mul_f32_e32 v34, 0x3d372713, v50
	v_mul_f32_e32 v34, v50, v34
	v_fma_f32 v34, v50, v34, v50
	v_mul_f32_e32 v34, 0x3f4c422a, v34
	v_add_f32_e32 v34, v34, v34
	v_mul_f32_e32 v34, 0xbfb8aa3b, v34
	v_cvt_f32_i32_e32 v24, v24
	v_exp_f32_e32 v34, v34
	v_mov_b32_e32 v48, v190
	v_mov_b32_e32 v49, v190
	v_pk_mul_f32 v[24:25], v[160:161], v[24:25]
	v_add_f32_e32 v34, 1.0, v34
	v_mov_b32_e32 v45, v35
	v_pk_mul_f32 v[24:25], v[48:49], v[24:25]
	v_rcp_f32_e32 v48, v34
	v_fma_f32 v47, v79, v47, v75
	v_pk_mul_f32 v[34:35], v[66:67], v[44:45]
	v_cvt_f32_i32_e32 v23, v23
	v_add_f32_e32 v35, v35, v47
	v_add_f32_e32 v44, v34, v35
	v_mul_f32_e32 v34, 0x3d372713, v44
	v_mul_f32_e32 v34, v44, v34
	v_fma_f32 v34, v44, v34, v44
	v_mul_f32_e32 v34, 0x3f4c422a, v34
	v_add_f32_e32 v34, v34, v34
	v_cvt_f32_i32_e32 v22, v22
	v_mul_f32_e32 v34, 0xbfb8aa3b, v34
	v_exp_f32_e32 v34, v34
	v_mul_f32_e32 v35, v50, v48
	v_pk_mul_f32 v[22:23], v[158:159], v[22:23]
	v_mov_b32_e32 v53, v36
	v_pk_mul_f32 v[22:23], v[190:191], v[22:23]
	v_add_f32_e32 v34, 1.0, v34
	v_mul_f32_e32 v22, v22, v35
	v_rcp_f32_e32 v45, v34
	v_fma_f32 v43, v80, v43, v76
	v_pk_mul_f32 v[34:35], v[92:93], v[52:53]
	v_fmac_f32_e32 v77, v81, v46
	v_add_f32_e32 v35, v35, v43
	v_add_f32_e32 v36, v34, v35
	v_mul_f32_e32 v34, 0x3d372713, v36
	v_mul_f32_e32 v34, v36, v34
	v_fma_f32 v34, v36, v34, v36
	v_mul_f32_e32 v34, 0x3f4c422a, v34
	v_add_f32_e32 v34, v34, v34
	v_mul_f32_e32 v34, 0xbfb8aa3b, v34
	v_mov_b32_e32 v43, v37
	v_exp_f32_e32 v47, v34
	v_pk_mul_f32 v[34:35], v[68:69], v[42:43]
	v_mul_f32_e32 v37, v44, v45
	v_add_f32_e32 v35, v35, v77
	v_add_f32_e32 v34, v34, v35
	v_mul_f32_e32 v35, 0x3d372713, v34
	v_mul_f32_e32 v35, v34, v35
	v_fma_f32 v35, v34, v35, v34
	v_mul_f32_e32 v35, 0x3f4c422a, v35
	v_add_f32_e32 v35, v35, v35
	v_mul_f32_e32 v35, 0xbfb8aa3b, v35
	v_exp_f32_e32 v35, v35
	v_add_f32_e32 v42, 1.0, v47
	v_rcp_f32_e32 v42, v42
	v_mul_f32_e32 v23, v23, v37
	v_add_f32_e32 v35, 1.0, v35
	v_rcp_f32_e32 v35, v35
	v_mul_f32_e32 v36, v36, v42
	v_mul_f32_e32 v24, v24, v36
	v_cvt_pk_bf16_f32 v22, v22, v23
	v_mul_f32_e32 v34, v34, v35
	v_mul_f32_e32 v25, v25, v34
	v_cvt_pk_bf16_f32 v23, v24, v25
	v_mov_b64_e32 v[24:25], s[24:25]
	v_mad_i64_i32 v[24:25], s[2:3], v201, s83, v[24:25]
	v_lshl_add_u64 v[64:65], v[194:195], 1, v[24:25]
	global_store_dwordx2 v[64:65], v[22:23], off
	global_load_dwordx4 v[42:45], v[202:203], off offset:16
	s_nop 0
	global_load_dwordx4 v[22:25], v[126:127], off
	global_load_dwordx4 v[46:49], v[128:129], off
	global_load_dwordx4 v[34:37], v[204:205], off offset:16
	s_mov_b64 s[2:3], -1
	s_and_b64 vcc, exec, s[62:63]
	s_cbranch_vccz .LBB0_2704
	s_waitcnt lgkmcnt(0)
	v_cndmask_b32_e64 v51, v38, v58, s[16:17]
	v_cndmask_b32_e64 v52, v39, v59, s[16:17]
	s_nop 0
	v_mov_b32_dpp v50, v51 row_ror:1 row_mask:0xf bank_mask:0xf
	v_cndmask_b32_e64 v51, v58, v38, s[38:39]
	v_cndmask_b32_e64 v53, v40, v60, s[16:17]
	s_nop 0
	v_mov_b32_dpp v69, v51 row_ror:2 row_mask:0xf bank_mask:0xf
	v_cndmask_b32_e64 v54, v41, v61, s[16:17]
	v_mov_b32_dpp v51, v52 row_ror:1 row_mask:0xf bank_mask:0xf
	v_cndmask_b32_e64 v52, v59, v39, s[38:39]
	s_mov_b64 s[2:3], 0
	s_nop 0
	v_mov_b32_dpp v67, v52 row_ror:2 row_mask:0xf bank_mask:0xf
	v_mov_b32_e32 v72, v38
	v_mov_b32_e32 v68, v39
	v_mov_b32_dpp v52, v53 row_ror:1 row_mask:0xf bank_mask:0xf
	v_cndmask_b32_e64 v53, v60, v40, s[38:39]
	v_mov_b32_e32 v66, v40
	v_mov_b32_e32 v56, v41
	v_mov_b32_dpp v57, v53 row_ror:2 row_mask:0xf bank_mask:0xf
	s_nop 1
	v_mov_b32_dpp v53, v54 row_ror:1 row_mask:0xf bank_mask:0xf
	v_cndmask_b32_e64 v54, v61, v41, s[38:39]
	s_nop 1
	v_mov_b32_dpp v74, v54 row_ror:2 row_mask:0xf bank_mask:0xf

; __device__ __forceinline__ unsigned cvt_pk_bf16(float lo, float hi) { unsigned r; asm("v_cvt_pk_bf16_f32 %0, %1, %2" : "=v"(r) : "v"(lo), "v"(hi)); return r; }
; __device__ __forceinline__ float gelu_tanh(float x) { const float u = 0.7978845608028654f * (x + 0.044715f * x * x * x); return x * sigmoidf_(2.0f * u); }
; __device__ __forceinline__ float dpp_ror1(float v) { return __builtin_bit_cast(float, __builtin_amdgcn_update_dpp(0, __builtin_bit_cast(int, v), 0x121, 0xf, 0xf, false)); }
; __device__ __forceinline__ float dpp_ror2(float v) { return __builtin_bit_cast(float, __builtin_amdgcn_update_dpp(0, __builtin_bit_cast(int, v), 0x122, 0xf, 0xf, false)); }
;     __device__ __forceinline__ void operator()(f32x4 (&acc)[2][2][4][2], const pg8::Unit& u, int wr, int wc, int fr, int fq) const {
;     ...
;             for (int n = 0; n < 2; ++n) {
;                 const f32x4 w0 = *(const f32x4*)(cw + ch0 + 4 * n), w1 = *(const f32x4*)(cw + DFF + ch0 + 4 * n), w2 = *(const f32x4*)(cw + 2 * DFF + ch0 + 4 * n), bb = *(const f32x4*)(cb + ch0 + 4 * n);
; #pragma unroll
;                 for (int m = 0; m < 4; ++m) { const int row = row0 + ai * 128 + m * 16; const f32x4 g = acc[ai][0][m][n], vv = acc[ai][1][m][n]; f32x4 p1, p2;
;                     if (prompt) { const f32x4 gp = (m == 0) ? hal[n] : acc[ai][0][m > 0 ? m - 1 : 0][n];
; #pragma unroll
;                         for (int j = 0; j < 4; ++j) { p1[j] = dpp_ror1(fr == 15 ? gp[j] : g[j]); p2[j] = dpp_ror2(fr >= 14 ? gp[j] : g[j]); } }
;                     else { const int t = fr & 3; const float* sp = stf + (size_t)((row - MP) >> 2) * 2 * DFF + ch0 + 4 * n;
;                         f32x4 b0 = (f32x4){0.f, 0.f, 0.f, 0.f}, b1 = b0; if (t == 0) b0 = *(const f32x4*)sp; if (t <= 1) b1 = *(const f32x4*)(sp + DFF);
; #pragma unroll
;                         for (int j = 0; j < 4; ++j) { const float r1 = dpp_ror1(g[j]), r2 = dpp_ror2(g[j]); p1[j] = t >= 1 ? r1 : b1[j]; p2[j] = t >= 2 ? r2 : (t == 1 ? b1[j] : b0[j]); } }
;                     float o[4];
; #pragma unroll
;                     for (int j = 0; j < 4; ++j) { const float y = bb[j] + w0[j] * p2[j] + w1[j] * p1[j] + w2[j] * g[j]; o[j] = gelu_tanh(y) * vv[j]; }
;                     u32x2 w; w.x = cvt_pk_bf16(o[0], o[1]); w.y = cvt_pk_bf16(o[2], o[3]);
;                     *(u32x2*)(ACT + (size_t)row * DFF + ch0 + 4 * n) = w; } } }
.LBB0_2709:
	s_or_b64 exec, exec, s[2:3]
	s_waitcnt vmcnt(0)
	v_cndmask_b32_e64 v52, v52, v56, s[14:15]
	v_cndmask_b32_e64 v53, v53, v57, s[14:15]
	v_mov_b32_dpp v51, v38 row_ror:2 row_mask:0xf bank_mask:0xf
	v_cndmask_b32_e64 v69, v52, v51, s[12:13]
	v_cndmask_b32_e64 v54, v54, v58, s[14:15]
	v_mov_b32_dpp v52, v39 row_ror:2 row_mask:0xf bank_mask:0xf
	v_cndmask_b32_e64 v67, v53, v52, s[12:13]
	v_mov_b32_dpp v51, v39 row_ror:1 row_mask:0xf bank_mask:0xf
	v_mov_b32_dpp v53, v40 row_ror:2 row_mask:0xf bank_mask:0xf
	v_cndmask_b32_e64 v51, v51, v57, s[10:11]
	v_cndmask_b32_e64 v57, v54, v53, s[12:13]
	v_mov_b32_dpp v50, v38 row_ror:1 row_mask:0xf bank_mask:0xf
	v_mov_b32_dpp v52, v40 row_ror:1 row_mask:0xf bank_mask:0xf
	v_mov_b32_dpp v53, v41 row_ror:1 row_mask:0xf bank_mask:0xf
	v_mov_b32_dpp v54, v41 row_ror:2 row_mask:0xf bank_mask:0xf
	v_cndmask_b32_e64 v55, v55, v59, s[14:15]
	v_cndmask_b32_e64 v50, v50, v56, s[10:11]
	v_cndmask_b32_e64 v52, v52, v58, s[10:11]
	v_cndmask_b32_e64 v53, v53, v59, s[10:11]
	v_cndmask_b32_e64 v74, v55, v54, s[12:13]
	v_mov_b32_e32 v72, v38
	v_mov_b32_e32 v68, v39
	v_mov_b32_e32 v66, v40
	v_mov_b32_e32 v56, v41
.LBB0_2710:
	s_waitcnt vmcnt(1)
	v_mov_b32_e32 v54, v46
	v_mov_b32_e32 v55, v22
	v_mov_b32_e32 v73, v50
	s_waitcnt vmcnt(0) lgkmcnt(0)
	v_fma_f32 v60, v42, v69, v34
	v_pk_mul_f32 v[58:59], v[54:55], v[72:73]
	v_cvt_f32_i32_e32 v17, v17
	v_add_f32_e32 v22, v59, v60
	v_add_f32_e32 v50, v58, v22
	v_mul_f32_e32 v22, 0x3d372713, v50
	v_mul_f32_e32 v22, v50, v22
	v_fma_f32 v22, v50, v22, v50
	v_mul_f32_e32 v22, 0x3f4c422a, v22
	v_add_f32_e32 v22, v22, v22
	v_mul_f32_e32 v22, 0xbfb8aa3b, v22
	v_cvt_f32_i32_e32 v16, v16
	v_exp_f32_e32 v22, v22
	v_mov_b32_e32 v58, v198
	v_mov_b32_e32 v59, v198
	v_pk_mul_f32 v[16:17], v[124:125], v[16:17]
	v_add_f32_e32 v22, 1.0, v22
	v_pk_mul_f32 v[16:17], v[58:59], v[16:17]
	v_rcp_f32_e32 v58, v22
	v_mov_b32_e32 v22, v47
	v_mov_b32_e32 v69, v51
	v_fma_f32 v59, v43, v67, v35
	v_pk_mul_f32 v[46:47], v[22:23], v[68:69]
	v_cvt_f32_i32_e32 v15, v15
	v_add_f32_e32 v47, v47, v59
	v_add_f32_e32 v59, v46, v47
	v_mul_f32_e32 v46, 0x3d372713, v59
	v_mul_f32_e32 v46, v59, v46
	v_fma_f32 v46, v59, v46, v59
	v_mul_f32_e32 v46, 0x3f4c422a, v46
	v_add_f32_e32 v46, v46, v46
	v_cvt_f32_i32_e32 v14, v14
	v_mul_f32_e32 v46, 0xbfb8aa3b, v46
	v_exp_f32_e32 v46, v46
	v_mul_f32_e32 v47, v50, v58
	v_pk_mul_f32 v[14:15], v[122:123], v[14:15]
	v_mov_b32_e32 v50, v48
	v_pk_mul_f32 v[14:15], v[198:199], v[14:15]
	v_add_f32_e32 v46, 1.0, v46
	v_mov_b32_e32 v51, v24
	v_mov_b32_e32 v67, v52
	v_mul_f32_e32 v14, v14, v47
	v_rcp_f32_e32 v58, v46
	v_fma_f32 v57, v44, v57, v36
	v_pk_mul_f32 v[46:47], v[50:51], v[66:67]
	v_fma_f32 v60, v45, v74, v37
	v_add_f32_e32 v24, v47, v57
	v_add_f32_e32 v48, v46, v24
	v_mul_f32_e32 v24, 0x3d372713, v48
	v_mul_f32_e32 v24, v48, v24
	v_fma_f32 v24, v48, v24, v48
	v_mul_f32_e32 v24, 0x3f4c422a, v24
	v_add_f32_e32 v24, v24, v24
	v_mul_f32_e32 v24, 0xbfb8aa3b, v24
	v_exp_f32_e32 v52, v24
	v_mov_b32_e32 v24, v49
	v_mov_b32_e32 v57, v53
	v_pk_mul_f32 v[46:47], v[24:25], v[56:57]
	v_add_f32_e32 v52, 1.0, v52
	v_add_f32_e32 v47, v47, v60
	v_add_f32_e32 v46, v46, v47
	v_mul_f32_e32 v47, 0x3d372713, v46
	v_mul_f32_e32 v47, v46, v47
	v_fma_f32 v47, v46, v47, v46
	v_mul_f32_e32 v47, 0x3f4c422a, v47
	v_add_f32_e32 v47, v47, v47
	v_mul_f32_e32 v47, 0xbfb8aa3b, v47
	v_exp_f32_e32 v47, v47
	v_rcp_f32_e32 v52, v52
	v_mul_f32_e32 v49, v59, v58
	v_mul_f32_e32 v15, v15, v49
	v_add_f32_e32 v47, 1.0, v47
	v_rcp_f32_e32 v47, v47
	v_mul_f32_e32 v48, v48, v52
	v_mul_f32_e32 v16, v16, v48
	v_cvt_pk_bf16_f32 v14, v14, v15
	v_mul_f32_e32 v46, v46, v47
	v_mul_f32_e32 v17, v17, v46
	v_cvt_pk_bf16_f32 v15, v16, v17
	s_mov_b64 s[2:3], -1
	s_and_b64 vcc, exec, s[62:63]
	global_store_dwordx2 v[86:87], v[14:15], off offset:8
	s_cbranch_vccz .LBB0_2712
	v_cndmask_b32_e64 v15, v30, v38, s[16:17]
	v_cndmask_b32_e64 v16, v31, v39, s[16:17]
	s_nop 0
	v_mov_b32_dpp v14, v15 row_ror:1 row_mask:0xf bank_mask:0xf
	v_cndmask_b32_e64 v15, v38, v30, s[38:39]
	v_cndmask_b32_e64 v17, v32, v40, s[16:17]
	s_nop 0
	v_mov_b32_dpp v57, v15 row_ror:2 row_mask:0xf bank_mask:0xf
	v_cndmask_b32_e64 v38, v33, v41, s[16:17]
	v_mov_b32_dpp v15, v16 row_ror:1 row_mask:0xf bank_mask:0xf
	v_cndmask_b32_e64 v16, v39, v31, s[38:39]
	s_mov_b64 s[2:3], 0
	s_nop 0
	v_mov_b32_dpp v53, v16 row_ror:2 row_mask:0xf bank_mask:0xf
	v_mov_b32_e32 v56, v30
	v_mov_b32_e32 v52, v31
	v_mov_b32_dpp v16, v17 row_ror:1 row_mask:0xf bank_mask:0xf
	v_cndmask_b32_e64 v17, v40, v32, s[38:39]
	v_mov_b32_e32 v48, v32
	v_mov_b32_e32 v46, v33
	v_mov_b32_dpp v47, v17 row_ror:2 row_mask:0xf bank_mask:0xf
	s_nop 1
	v_mov_b32_dpp v17, v38 row_ror:1 row_mask:0xf bank_mask:0xf
	v_cndmask_b32_e64 v38, v41, v33, s[38:39]
	s_nop 1
	v_mov_b32_dpp v58, v38 row_ror:2 row_mask:0xf bank_mask:0xf

; __device__ __forceinline__ unsigned cvt_pk_bf16(float lo, float hi) { unsigned r; asm("v_cvt_pk_bf16_f32 %0, %1, %2" : "=v"(r) : "v"(lo), "v"(hi)); return r; }
; __device__ __forceinline__ float gelu_tanh(float x) { const float u = 0.7978845608028654f * (x + 0.044715f * x * x * x); return x * sigmoidf_(2.0f * u); }
; __device__ __forceinline__ float dpp_ror1(float v) { return __builtin_bit_cast(float, __builtin_amdgcn_update_dpp(0, __builtin_bit_cast(int, v), 0x121, 0xf, 0xf, false)); }
; __device__ __forceinline__ float dpp_ror2(float v) { return __builtin_bit_cast(float, __builtin_amdgcn_update_dpp(0, __builtin_bit_cast(int, v), 0x122, 0xf, 0xf, false)); }
;     __device__ __forceinline__ void operator()(f32x4 (&acc)[2][2][4][2], const pg8::Unit& u, int wr, int wc, int fr, int fq) const {
;     ...
;             for (int n = 0; n < 2; ++n) {
;                 const f32x4 w0 = *(const f32x4*)(cw + ch0 + 4 * n), w1 = *(const f32x4*)(cw + DFF + ch0 + 4 * n), w2 = *(const f32x4*)(cw + 2 * DFF + ch0 + 4 * n), bb = *(const f32x4*)(cb + ch0 + 4 * n);
; #pragma unroll
;                 for (int m = 0; m < 4; ++m) { const int row = row0 + ai * 128 + m * 16; const f32x4 g = acc[ai][0][m][n], vv = acc[ai][1][m][n]; f32x4 p1, p2;
;                     if (prompt) { const f32x4 gp = (m == 0) ? hal[n] : acc[ai][0][m > 0 ? m - 1 : 0][n];
; #pragma unroll
;                         for (int j = 0; j < 4; ++j) { p1[j] = dpp_ror1(fr == 15 ? gp[j] : g[j]); p2[j] = dpp_ror2(fr >= 14 ? gp[j] : g[j]); } }
;                     else { const int t = fr & 3; const float* sp = stf + (size_t)((row - MP) >> 2) * 2 * DFF + ch0 + 4 * n;
;                         f32x4 b0 = (f32x4){0.f, 0.f, 0.f, 0.f}, b1 = b0; if (t == 0) b0 = *(const f32x4*)sp; if (t <= 1) b1 = *(const f32x4*)(sp + DFF);
; #pragma unroll
;                         for (int j = 0; j < 4; ++j) { const float r1 = dpp_ror1(g[j]), r2 = dpp_ror2(g[j]); p1[j] = t >= 1 ? r1 : b1[j]; p2[j] = t >= 2 ? r2 : (t == 1 ? b1[j] : b0[j]); } }
;                     float o[4];
; #pragma unroll
;                     for (int j = 0; j < 4; ++j) { const float y = bb[j] + w0[j] * p2[j] + w1[j] * p1[j] + w2[j] * g[j]; o[j] = gelu_tanh(y) * vv[j]; }
;                     u32x2 w; w.x = cvt_pk_bf16(o[0], o[1]); w.y = cvt_pk_bf16(o[2], o[3]);
;                     *(u32x2*)(ACT + (size_t)row * DFF + ch0 + 4 * n) = w; } } }
.LBB0_2717:
	s_or_b64 exec, exec, s[2:3]
	s_waitcnt vmcnt(0)
	v_cndmask_b32_e64 v16, v38, v46, s[14:15]
	v_cndmask_b32_e64 v17, v39, v47, s[14:15]
	v_mov_b32_dpp v15, v30 row_ror:2 row_mask:0xf bank_mask:0xf
	v_cndmask_b32_e64 v57, v16, v15, s[12:13]
	v_cndmask_b32_e64 v38, v40, v48, s[14:15]
	v_mov_b32_dpp v16, v31 row_ror:2 row_mask:0xf bank_mask:0xf
	v_cndmask_b32_e64 v53, v17, v16, s[12:13]
	v_mov_b32_dpp v15, v31 row_ror:1 row_mask:0xf bank_mask:0xf
	v_mov_b32_dpp v17, v32 row_ror:2 row_mask:0xf bank_mask:0xf
	v_cndmask_b32_e64 v15, v15, v47, s[10:11]
	v_cndmask_b32_e64 v47, v38, v17, s[12:13]
	v_mov_b32_dpp v14, v30 row_ror:1 row_mask:0xf bank_mask:0xf
	v_mov_b32_dpp v16, v32 row_ror:1 row_mask:0xf bank_mask:0xf
	v_mov_b32_dpp v17, v33 row_ror:1 row_mask:0xf bank_mask:0xf
	v_mov_b32_dpp v38, v33 row_ror:2 row_mask:0xf bank_mask:0xf
	v_cndmask_b32_e64 v39, v41, v49, s[14:15]
	v_cndmask_b32_e64 v14, v14, v46, s[10:11]
	v_cndmask_b32_e64 v16, v16, v48, s[10:11]
	v_cndmask_b32_e64 v17, v17, v49, s[10:11]
	v_cndmask_b32_e64 v58, v39, v38, s[12:13]
	v_mov_b32_e32 v56, v30
	v_mov_b32_e32 v52, v31
	v_mov_b32_e32 v48, v32
	v_mov_b32_e32 v46, v33
.LBB0_2718:
	v_fma_f32 v40, v42, v57, v34
	v_mov_b32_e32 v57, v14
	v_pk_mul_f32 v[38:39], v[54:55], v[56:57]
	v_cvt_f32_i32_e32 v13, v13
	v_add_f32_e32 v14, v39, v40
	v_add_f32_e32 v40, v38, v14
	v_mul_f32_e32 v14, 0x3d372713, v40
	v_mul_f32_e32 v14, v40, v14
	v_fma_f32 v14, v40, v14, v40
	v_mul_f32_e32 v14, 0x3f4c422a, v14
	v_add_f32_e32 v14, v14, v14
	v_cvt_f32_i32_e32 v12, v12
	v_mul_f32_e32 v14, 0xbfb8aa3b, v14
	v_exp_f32_e32 v14, v14
	v_mov_b32_e32 v38, v196
	v_pk_mul_f32 v[12:13], v[124:125], v[12:13]
	v_mov_b32_e32 v39, v196
	v_pk_mul_f32 v[12:13], v[38:39], v[12:13]
	v_add_f32_e32 v14, 1.0, v14
	v_fma_f32 v39, v43, v53, v35
	v_mov_b32_e32 v53, v15
	v_rcp_f32_e32 v38, v14
	v_pk_mul_f32 v[14:15], v[22:23], v[52:53]
	v_cvt_f32_i32_e32 v11, v11
	v_add_f32_e32 v15, v15, v39
	v_add_f32_e32 v39, v14, v15
	v_mul_f32_e32 v14, 0x3d372713, v39
	v_mul_f32_e32 v14, v39, v14
	v_fma_f32 v14, v39, v14, v39
	v_mul_f32_e32 v14, 0x3f4c422a, v14
	v_add_f32_e32 v14, v14, v14
	v_cvt_f32_i32_e32 v10, v10
	v_mul_f32_e32 v14, 0xbfb8aa3b, v14
	v_exp_f32_e32 v14, v14
	v_mul_f32_e32 v15, v40, v38
	v_pk_mul_f32 v[10:11], v[122:123], v[10:11]
	v_mov_b32_e32 v49, v16
	v_pk_mul_f32 v[10:11], v[196:197], v[10:11]
	v_add_f32_e32 v14, 1.0, v14
	v_mul_f32_e32 v10, v10, v15
	v_rcp_f32_e32 v38, v14
	v_fma_f32 v40, v44, v47, v36
	v_pk_mul_f32 v[14:15], v[50:51], v[48:49]
	v_mov_b32_e32 v47, v17
	v_add_f32_e32 v15, v15, v40
	v_add_f32_e32 v16, v14, v15
	v_mul_f32_e32 v14, 0x3d372713, v16
	v_mul_f32_e32 v14, v16, v14
	v_fma_f32 v14, v16, v14, v16
	v_mul_f32_e32 v14, 0x3f4c422a, v14
	v_add_f32_e32 v14, v14, v14
	v_mul_f32_e32 v14, 0xbfb8aa3b, v14
	v_exp_f32_e32 v40, v14
	v_fma_f32 v41, v45, v58, v37
	v_pk_mul_f32 v[14:15], v[24:25], v[46:47]
	v_mul_f32_e32 v17, v39, v38
	v_add_f32_e32 v15, v15, v41
	v_add_f32_e32 v14, v14, v15
	v_mul_f32_e32 v15, 0x3d372713, v14
	v_mul_f32_e32 v15, v14, v15
	v_fma_f32 v15, v14, v15, v14
	v_mul_f32_e32 v15, 0x3f4c422a, v15
	v_add_f32_e32 v15, v15, v15
	v_mul_f32_e32 v15, 0xbfb8aa3b, v15
	v_exp_f32_e32 v15, v15
	v_add_f32_e32 v38, 1.0, v40
	v_rcp_f32_e32 v38, v38
	v_mul_f32_e32 v11, v11, v17
	v_add_f32_e32 v15, 1.0, v15
	v_rcp_f32_e32 v15, v15
	v_mul_f32_e32 v16, v16, v38
	v_mul_f32_e32 v12, v12, v16
	v_cvt_pk_bf16_f32 v10, v10, v11
	v_mul_f32_e32 v14, v14, v15
	v_mul_f32_e32 v13, v13, v14
	v_cvt_pk_bf16_f32 v11, v12, v13
	s_mov_b64 s[2:3], -1
	s_and_b64 vcc, exec, s[62:63]
	global_store_dwordx2 v[70:71], v[10:11], off offset:8
	s_cbranch_vccz .LBB0_2720
	v_cndmask_b32_e64 v11, v26, v30, s[16:17]
	v_cndmask_b32_e64 v12, v27, v31, s[16:17]
	s_nop 0
	v_mov_b32_dpp v10, v11 row_ror:1 row_mask:0xf bank_mask:0xf
	v_cndmask_b32_e64 v11, v30, v26, s[38:39]
	v_cndmask_b32_e64 v13, v28, v32, s[16:17]
	s_nop 0
	v_mov_b32_dpp v41, v11 row_ror:2 row_mask:0xf bank_mask:0xf
	v_cndmask_b32_e64 v14, v29, v33, s[16:17]
	v_mov_b32_dpp v11, v12 row_ror:1 row_mask:0xf bank_mask:0xf
	v_cndmask_b32_e64 v12, v31, v27, s[38:39]
	s_mov_b64 s[2:3], 0
	s_nop 0
	v_mov_b32_dpp v39, v12 row_ror:2 row_mask:0xf bank_mask:0xf
	v_mov_b32_e32 v40, v26
	v_mov_b32_e32 v38, v27
	v_mov_b32_dpp v12, v13 row_ror:1 row_mask:0xf bank_mask:0xf
	v_cndmask_b32_e64 v13, v32, v28, s[38:39]
	v_mov_b32_e32 v16, v28
	s_nop 0
	v_mov_b32_dpp v17, v13 row_ror:2 row_mask:0xf bank_mask:0xf
	s_nop 1
	v_mov_b32_dpp v13, v14 row_ror:1 row_mask:0xf bank_mask:0xf
	v_cndmask_b32_e64 v14, v33, v29, s[38:39]
	s_nop 1
	v_mov_b32_dpp v15, v14 row_ror:2 row_mask:0xf bank_mask:0xf
	v_mov_b32_e32 v14, v29

; __device__ __forceinline__ unsigned cvt_pk_bf16(float lo, float hi) { unsigned r; asm("v_cvt_pk_bf16_f32 %0, %1, %2" : "=v"(r) : "v"(lo), "v"(hi)); return r; }
; __device__ __forceinline__ float gelu_tanh(float x) { const float u = 0.7978845608028654f * (x + 0.044715f * x * x * x); return x * sigmoidf_(2.0f * u); }
; __device__ __forceinline__ float dpp_ror1(float v) { return __builtin_bit_cast(float, __builtin_amdgcn_update_dpp(0, __builtin_bit_cast(int, v), 0x121, 0xf, 0xf, false)); }
; __device__ __forceinline__ float dpp_ror2(float v) { return __builtin_bit_cast(float, __builtin_amdgcn_update_dpp(0, __builtin_bit_cast(int, v), 0x122, 0xf, 0xf, false)); }
;     __device__ __forceinline__ void operator()(f32x4 (&acc)[2][2][4][2], const pg8::Unit& u, int wr, int wc, int fr, int fq) const {
;     ...
;             for (int n = 0; n < 2; ++n) {
;                 const f32x4 w0 = *(const f32x4*)(cw + ch0 + 4 * n), w1 = *(const f32x4*)(cw + DFF + ch0 + 4 * n), w2 = *(const f32x4*)(cw + 2 * DFF + ch0 + 4 * n), bb = *(const f32x4*)(cb + ch0 + 4 * n);
; #pragma unroll
;                 for (int m = 0; m < 4; ++m) { const int row = row0 + ai * 128 + m * 16; const f32x4 g = acc[ai][0][m][n], vv = acc[ai][1][m][n]; f32x4 p1, p2;
;                     if (prompt) { const f32x4 gp = (m == 0) ? hal[n] : acc[ai][0][m > 0 ? m - 1 : 0][n];
; #pragma unroll
;                         for (int j = 0; j < 4; ++j) { p1[j] = dpp_ror1(fr == 15 ? gp[j] : g[j]); p2[j] = dpp_ror2(fr >= 14 ? gp[j] : g[j]); } }
;                     else { const int t = fr & 3; const float* sp = stf + (size_t)((row - MP) >> 2) * 2 * DFF + ch0 + 4 * n;
;                         f32x4 b0 = (f32x4){0.f, 0.f, 0.f, 0.f}, b1 = b0; if (t == 0) b0 = *(const f32x4*)sp; if (t <= 1) b1 = *(const f32x4*)(sp + DFF);
; #pragma unroll
;                         for (int j = 0; j < 4; ++j) { const float r1 = dpp_ror1(g[j]), r2 = dpp_ror2(g[j]); p1[j] = t >= 1 ? r1 : b1[j]; p2[j] = t >= 2 ? r2 : (t == 1 ? b1[j] : b0[j]); } }
;                     float o[4];
; #pragma unroll
;                     for (int j = 0; j < 4; ++j) { const float y = bb[j] + w0[j] * p2[j] + w1[j] * p1[j] + w2[j] * g[j]; o[j] = gelu_tanh(y) * vv[j]; }
;                     u32x2 w; w.x = cvt_pk_bf16(o[0], o[1]); w.y = cvt_pk_bf16(o[2], o[3]);
;                     *(u32x2*)(ACT + (size_t)row * DFF + ch0 + 4 * n) = w; } } }
.LBB0_2725:
	s_or_b64 exec, exec, s[2:3]
	s_waitcnt vmcnt(0)
	v_cndmask_b32_e64 v12, v12, v30, s[14:15]
	v_cndmask_b32_e64 v13, v13, v31, s[14:15]
	v_mov_b32_dpp v11, v26 row_ror:2 row_mask:0xf bank_mask:0xf
	v_cndmask_b32_e64 v41, v12, v11, s[12:13]
	v_cndmask_b32_e64 v14, v14, v32, s[14:15]
	v_mov_b32_dpp v12, v27 row_ror:2 row_mask:0xf bank_mask:0xf
	v_cndmask_b32_e64 v39, v13, v12, s[12:13]
	v_mov_b32_dpp v13, v28 row_ror:2 row_mask:0xf bank_mask:0xf
	v_cndmask_b32_e64 v17, v14, v13, s[12:13]
	v_mov_b32_dpp v10, v26 row_ror:1 row_mask:0xf bank_mask:0xf
	v_mov_b32_dpp v11, v27 row_ror:1 row_mask:0xf bank_mask:0xf
	v_mov_b32_dpp v12, v28 row_ror:1 row_mask:0xf bank_mask:0xf
	v_mov_b32_dpp v13, v29 row_ror:1 row_mask:0xf bank_mask:0xf
	v_mov_b32_dpp v14, v29 row_ror:2 row_mask:0xf bank_mask:0xf
	v_cndmask_b32_e64 v15, v15, v33, s[14:15]
	v_cndmask_b32_e64 v10, v10, v30, s[10:11]
	v_cndmask_b32_e64 v11, v11, v31, s[10:11]
	v_cndmask_b32_e64 v12, v12, v32, s[10:11]
	v_cndmask_b32_e64 v13, v13, v33, s[10:11]
	v_cndmask_b32_e64 v15, v15, v14, s[12:13]
	v_mov_b32_e32 v40, v26
	v_mov_b32_e32 v38, v27
	v_mov_b32_e32 v16, v28
	v_mov_b32_e32 v14, v29
.LBB0_2726:
	v_fma_f32 v32, v42, v41, v34
	v_mov_b32_e32 v41, v10
	v_pk_mul_f32 v[30:31], v[54:55], v[40:41]
	v_cvt_f32_i32_e32 v9, v9
	v_add_f32_e32 v10, v31, v32
	v_add_f32_e32 v32, v30, v10
	v_mul_f32_e32 v10, 0x3d372713, v32
	v_mul_f32_e32 v10, v32, v10
	v_fma_f32 v10, v32, v10, v32
	v_mul_f32_e32 v10, 0x3f4c422a, v10
	v_add_f32_e32 v10, v10, v10
	v_cvt_f32_i32_e32 v8, v8
	v_mul_f32_e32 v10, 0xbfb8aa3b, v10
	v_exp_f32_e32 v10, v10
	v_mov_b32_e32 v30, v192
	v_pk_mul_f32 v[8:9], v[124:125], v[8:9]
	v_mov_b32_e32 v31, v192
	v_pk_mul_f32 v[8:9], v[30:31], v[8:9]
	v_add_f32_e32 v10, 1.0, v10
	v_fma_f32 v31, v43, v39, v35
	v_mov_b32_e32 v39, v11
	v_rcp_f32_e32 v30, v10
	v_pk_mul_f32 v[10:11], v[22:23], v[38:39]
	v_cvt_f32_i32_e32 v7, v7
	v_add_f32_e32 v11, v11, v31
	v_add_f32_e32 v31, v10, v11
	v_mul_f32_e32 v10, 0x3d372713, v31
	v_mul_f32_e32 v10, v31, v10
	v_fma_f32 v10, v31, v10, v31
	v_mul_f32_e32 v10, 0x3f4c422a, v10
	v_add_f32_e32 v10, v10, v10
	v_cvt_f32_i32_e32 v6, v6
	v_mul_f32_e32 v10, 0xbfb8aa3b, v10
	v_exp_f32_e32 v10, v10
	v_mul_f32_e32 v11, v32, v30
	v_pk_mul_f32 v[6:7], v[122:123], v[6:7]
	v_fma_f32 v32, v44, v17, v36
	v_pk_mul_f32 v[6:7], v[192:193], v[6:7]
	v_add_f32_e32 v10, 1.0, v10
	v_mov_b32_e32 v17, v12
	v_mul_f32_e32 v6, v6, v11
	v_rcp_f32_e32 v30, v10
	v_pk_mul_f32 v[10:11], v[50:51], v[16:17]
	v_fma_f32 v17, v45, v15, v37
	v_add_f32_e32 v11, v11, v32
	v_add_f32_e32 v12, v10, v11
	v_mul_f32_e32 v10, 0x3d372713, v12
	v_mul_f32_e32 v10, v12, v10
	v_fma_f32 v10, v12, v10, v12
	v_mul_f32_e32 v10, 0x3f4c422a, v10
	v_add_f32_e32 v10, v10, v10
	v_mul_f32_e32 v10, 0xbfb8aa3b, v10
	v_mov_b32_e32 v15, v13
	v_exp_f32_e32 v16, v10
	v_pk_mul_f32 v[10:11], v[24:25], v[14:15]
	v_mul_f32_e32 v13, v31, v30
	v_add_f32_e32 v11, v11, v17
	v_add_f32_e32 v10, v10, v11
	v_mul_f32_e32 v11, 0x3d372713, v10
	v_mul_f32_e32 v11, v10, v11
	v_fma_f32 v11, v10, v11, v10
	v_mul_f32_e32 v11, 0x3f4c422a, v11
	v_add_f32_e32 v11, v11, v11
	v_mul_f32_e32 v11, 0xbfb8aa3b, v11
	v_exp_f32_e32 v11, v11
	v_add_f32_e32 v14, 1.0, v16
	v_rcp_f32_e32 v14, v14
	v_mul_f32_e32 v7, v7, v13
	v_add_f32_e32 v11, 1.0, v11
	v_rcp_f32_e32 v11, v11
	v_mul_f32_e32 v12, v12, v14
	v_mul_f32_e32 v8, v8, v12
	v_cvt_pk_bf16_f32 v6, v6, v7
	v_mul_f32_e32 v10, v10, v11
	v_mul_f32_e32 v9, v9, v10
	v_cvt_pk_bf16_f32 v7, v8, v9
	s_mov_b64 s[2:3], -1
	s_and_b64 vcc, exec, s[62:63]
	global_store_dwordx2 v[62:63], v[6:7], off offset:8
	s_cbranch_vccz .LBB0_2728
	v_cndmask_b32_e64 v7, v18, v26, s[16:17]
	v_cndmask_b32_e64 v8, v19, v27, s[16:17]
	s_nop 0
	v_mov_b32_dpp v6, v7 row_ror:1 row_mask:0xf bank_mask:0xf
	v_cndmask_b32_e64 v7, v26, v18, s[38:39]
	v_cndmask_b32_e64 v9, v20, v28, s[16:17]
	s_nop 0
	v_mov_b32_dpp v16, v7 row_ror:2 row_mask:0xf bank_mask:0xf
	v_cndmask_b32_e64 v10, v21, v29, s[16:17]
	v_mov_b32_dpp v7, v8 row_ror:1 row_mask:0xf bank_mask:0xf
	v_cndmask_b32_e64 v8, v27, v19, s[38:39]
	s_mov_b64 s[2:3], 0
	s_nop 0
	v_mov_b32_dpp v13, v8 row_ror:2 row_mask:0xf bank_mask:0xf
	v_mov_b32_e32 v12, v19
	s_nop 0
	v_mov_b32_dpp v8, v9 row_ror:1 row_mask:0xf bank_mask:0xf
	v_cndmask_b32_e64 v9, v28, v20, s[38:39]
	s_nop 1
	v_mov_b32_dpp v14, v9 row_ror:2 row_mask:0xf bank_mask:0xf
	s_nop 1
	v_mov_b32_dpp v9, v10 row_ror:1 row_mask:0xf bank_mask:0xf
	v_cndmask_b32_e64 v10, v29, v21, s[38:39]
	s_nop 1
	v_mov_b32_dpp v11, v10 row_ror:2 row_mask:0xf bank_mask:0xf
	v_mov_b32_e32 v10, v21

; __device__ __forceinline__ float dpp_ror1(float v) { return __builtin_bit_cast(float, __builtin_amdgcn_update_dpp(0, __builtin_bit_cast(int, v), 0x121, 0xf, 0xf, false)); }
; __device__ __forceinline__ float dpp_ror2(float v) { return __builtin_bit_cast(float, __builtin_amdgcn_update_dpp(0, __builtin_bit_cast(int, v), 0x122, 0xf, 0xf, false)); }
;     __device__ __forceinline__ void operator()(f32x4 (&acc)[2][2][4][2], const pg8::Unit& u, int wr, int wc, int fr, int fq) const {
;     ...
;                     else { const int t = fr & 3; const float* sp = stf + (size_t)((row - MP) >> 2) * 2 * DFF + ch0 + 4 * n;
;                         f32x4 b0 = (f32x4){0.f, 0.f, 0.f, 0.f}, b1 = b0; if (t == 0) b0 = *(const f32x4*)sp; if (t <= 1) b1 = *(const f32x4*)(sp + DFF);
; #pragma unroll
;                         for (int j = 0; j < 4; ++j) { const float r1 = dpp_ror1(g[j]), r2 = dpp_ror2(g[j]); p1[j] = t >= 1 ? r1 : b1[j]; p2[j] = t >= 2 ? r2 : (t == 1 ? b1[j] : b0[j]); } }
.LBB0_2733:
	s_or_b64 exec, exec, s[2:3]
	s_waitcnt vmcnt(0)
	v_cndmask_b32_e64 v8, v8, v12, s[14:15]
	v_cndmask_b32_e64 v9, v9, v13, s[14:15]
	v_mov_b32_dpp v7, v18 row_ror:2 row_mask:0xf bank_mask:0xf
	v_cndmask_b32_e64 v16, v8, v7, s[12:13]
	v_cndmask_b32_e64 v10, v10, v14, s[14:15]
	v_mov_b32_dpp v7, v19 row_ror:1 row_mask:0xf bank_mask:0xf
	v_mov_b32_dpp v8, v19 row_ror:2 row_mask:0xf bank_mask:0xf
	v_cndmask_b32_e64 v7, v7, v13, s[10:11]
	v_cndmask_b32_e64 v13, v9, v8, s[12:13]
	v_mov_b32_dpp v8, v20 row_ror:1 row_mask:0xf bank_mask:0xf
	v_mov_b32_dpp v9, v20 row_ror:2 row_mask:0xf bank_mask:0xf
	v_cndmask_b32_e64 v8, v8, v14, s[10:11]
	v_cndmask_b32_e64 v14, v10, v9, s[12:13]
	v_mov_b32_dpp v6, v18 row_ror:1 row_mask:0xf bank_mask:0xf
	v_mov_b32_dpp v9, v21 row_ror:1 row_mask:0xf bank_mask:0xf
	v_mov_b32_dpp v10, v21 row_ror:2 row_mask:0xf bank_mask:0xf
	v_cndmask_b32_e64 v11, v11, v15, s[14:15]
	v_cndmask_b32_e64 v6, v6, v12, s[10:11]
	v_cndmask_b32_e64 v9, v9, v15, s[10:11]
	v_cndmask_b32_e64 v11, v11, v10, s[12:13]
	v_mov_b32_e32 v12, v19
	v_mov_b32_e32 v10, v21
